# v30 + in-projection QK-norm and out-projection epilogue row sums: the dependent shfl_xor 16/32 steps use permlane16/32 swaps instead of ds_bpermute round trips
# baseline (speedup 1.0000x reference)
; __device__ __forceinline__ float dot4(f32x4 a) { return (a[0] * a[0] + a[1] * a[1]) + (a[2] * a[2] + a[3] * a[3]); }
;     __device__ __forceinline__ void operator()(const f32x4 (&acc)[2][2][4][2], const Unit& u, int wr, int wc, int fr, int fq) const {
;     ...
;             const float* g = gqk + type * 128 + (wc & 1) * 64 + 8 * fq;
;             f32x4 gv[2][2];
; #pragma unroll
;             for (int bj = 0; bj < 2; ++bj)
; #pragma unroll
;                 for (int n = 0; n < 2; ++n) gv[bj][n] = *(const f32x4*)(g + 32 * bj + 4 * n);
;             const float sc = type == 0 ? QSCALE : 1.0f;
; #pragma unroll
;             for (int ai = 0; ai < 2; ++ai)
; #pragma unroll
;                 for (int m = 0; m < 4; ++m) {
;                     const int row = row0 + ai * HALF + m * 16; f32x4 v[2][2]; float ss = 0.f;
; #pragma unroll
;                     for (int bj = 0; bj < 2; ++bj)
; #pragma unroll
;                         for (int n = 0; n < 2; ++n) { v[bj][n] = acc[ai][bj][m][n]; ss += dot4(v[bj][n]); }
;                     ss += __shfl_xor(ss, 16); ss += __shfl_xor(ss, 32);
;                     const float rn = rsqrtf(ss * (1.0f / 64.0f) + EPS);
; #pragma unroll
;                     for (int bj = 0; bj < 2; ++bj) {
;                         const f32x4 a = v[bj][0] * rn * gv[bj][0], b = v[bj][1] * rn * gv[bj][1];
;                         if (type == 1) { float* ko = kvo + (size_t)(ai * HALF + m * 16) * 512 + cl + 32 * bj; *(f32x4*)ko = a; *(f32x4*)(ko + 4) = b; }
.LBB0_307:
	s_lshl_b32 s0, s49, 7
	s_ashr_i32 s1, s0, 31
	s_lshl_b64 s[0:1], s[0:1], 2
	s_add_u32 s0, s86, s0
	s_addc_u32 s1, s87, s1
	v_ashrrev_i32_e32 v187, 31, v186
	v_lshl_add_u64 v[134:135], v[186:187], 2, s[0:1]
	global_load_dwordx4 v[142:145], v[134:135], off
	global_load_dwordx4 v[138:141], v[134:135], off offset:16
	global_load_dwordx4 v[130:133], v[134:135], off offset:144
	s_nop 0
	global_load_dwordx4 v[134:137], v[134:135], off offset:128
	v_pk_mul_f32 v[146:147], v[128:129], v[128:129]
	v_pk_mul_f32 v[148:149], v[126:127], v[126:127]
	v_pk_mul_f32 v[150:151], v[124:125], v[124:125]
	v_pk_mul_f32 v[152:153], v[122:123], v[122:123]
	v_pk_mov_b32 v[158:159], v[148:149], v[146:147] op_sel:[1,0]
	v_mov_b32_e32 v149, v147
	v_pk_mov_b32 v[146:147], v[152:153], v[150:151] op_sel:[1,0]
	v_mov_b32_e32 v153, v151
	v_xor_b32_e32 v157, 16, v197
	v_and_b32_e32 v155, 64, v197
	v_mul_f32_e32 v154, v119, v119
	v_mul_f32_e32 v156, v121, v121
	v_pk_add_f32 v[148:149], v[158:159], v[148:149]
	v_pk_add_f32 v[146:147], v[146:147], v[152:153]
	v_mul_f32_e32 v160, v114, v114
	v_mul_f32_e32 v161, v115, v115
	v_mul_f32_e32 v181, v116, v116
	v_mul_f32_e32 v183, v117, v117
	v_add_u32_e32 v186, 64, v155
	v_pk_fma_f32 v[150:151], v[118:119], v[118:119], v[154:155] op_sel_hi:[1,1,0]
	v_pk_fma_f32 v[154:155], v[120:121], v[120:121], v[156:157] op_sel_hi:[1,1,0]
	v_pk_add_f32 v[148:149], v[148:149], v[148:149] op_sel:[0,1] op_sel_hi:[1,0]
	v_pk_add_f32 v[146:147], v[146:147], v[146:147] op_sel:[0,1] op_sel_hi:[1,0]
	v_mov_b32_e32 v151, v181
	v_mov_b32_e32 v155, v183
	v_mov_b32_e32 v149, v160
	v_mov_b32_e32 v147, v161
	v_cmp_lt_i32_e32 vcc, v157, v186
	v_pk_add_f32 v[150:151], v[150:151], v[154:155]
	v_pk_add_f32 v[146:147], v[148:149], v[146:147]
	v_cndmask_b32_e32 v156, v197, v157, vcc
	v_pk_add_f32 v[146:147], v[146:147], v[150:151]
	v_lshlrev_b32_e32 v152, 2, v156
	v_add_f32_e32 v146, v146, v147
	v_mov_b32_e32 v147, v146
	s_nop 1
	v_permlane16_swap_b32_e32 v147, v146
	v_xor_b32_e32 v148, 32, v197
	v_cmp_lt_i32_e32 vcc, v148, v186
	v_ashrrev_i32_e32 v181, 31, v180
	s_cmp_eq_u32 s49, 1
	v_cndmask_b32_e32 v148, v197, v148, vcc
	v_lshlrev_b32_e32 v153, 2, v148
	s_waitcnt lgkmcnt(0)
	v_add_f32_e32 v148, v146, v147
	v_mov_b32_e32 v149, v148
	s_nop 1
	v_permlane32_swap_b32_e32 v149, v148
	v_lshl_add_u64 v[146:147], v[180:181], 2, v[184:185]
	s_cselect_b64 s[70:71], -1, 0
	s_cmp_lg_u32 s49, 1
	s_waitcnt lgkmcnt(0)
	v_add_f32_e32 v148, v148, v149
	v_fmamk_f32 v148, v148, 0x3c800000, v195
	v_mul_f32_e32 v149, 0x4b800000, v148
	v_cmp_gt_f32_e32 vcc, s93, v148
	s_nop 1
	v_cndmask_b32_e32 v148, v148, v149, vcc
	v_rsq_f32_e32 v148, v148
	s_nop 0
	v_mul_f32_e32 v149, 0x45800000, v148
	v_cndmask_b32_e32 v150, v148, v149, vcc
	v_pk_mul_f32 v[126:127], v[126:127], v[150:151] op_sel_hi:[1,0]
	v_pk_mul_f32 v[128:129], v[128:129], v[150:151] op_sel_hi:[1,0]
	v_pk_mul_f32 v[122:123], v[122:123], v[150:151] op_sel_hi:[1,0]
	v_pk_mul_f32 v[124:125], v[124:125], v[150:151] op_sel_hi:[1,0]
	s_waitcnt vmcnt(0)
	v_pk_mul_f32 v[128:129], v[144:145], v[128:129]
	v_pk_mul_f32 v[126:127], v[142:143], v[126:127]
	v_pk_mul_f32 v[124:125], v[140:141], v[124:125]
	v_pk_mul_f32 v[122:123], v[138:139], v[122:123]
	s_cbranch_scc1 .LBB0_309
	global_store_dwordx4 v[146:147], v[126:129], off
	global_store_dwordx4 v[146:147], v[122:125], off offset:16

; __device__ __forceinline__ float dot4(f32x4 a) { return (a[0] * a[0] + a[1] * a[1]) + (a[2] * a[2] + a[3] * a[3]); }
; __device__ __forceinline__ u32x4 pack8(f32x4 a, f32x4 b) { u32x4 w; w.x = cvt_pk_bf16(a[0], a[1]); w.y = cvt_pk_bf16(a[2], a[3]); w.z = cvt_pk_bf16(b[0], b[1]); w.w = cvt_pk_bf16(b[2], b[3]); return w; }
;     __device__ __forceinline__ void operator()(const f32x4 (&acc)[2][2][4][2], const Unit& u, int wr, int wc, int fr, int fq) const {
;     ...
;                     const int row = row0 + ai * HALF + m * 16; f32x4 v[2][2]; float ss = 0.f;
; #pragma unroll
;                     for (int bj = 0; bj < 2; ++bj)
; #pragma unroll
;                         for (int n = 0; n < 2; ++n) { v[bj][n] = acc[ai][bj][m][n]; ss += dot4(v[bj][n]); }
;                     ss += __shfl_xor(ss, 16); ss += __shfl_xor(ss, 32);
;                     const float rn = rsqrtf(ss * (1.0f / 64.0f) + EPS);
; #pragma unroll
;                     for (int bj = 0; bj < 2; ++bj) {
;                         const f32x4 a = v[bj][0] * rn * gv[bj][0], b = v[bj][1] * rn * gv[bj][1];
;                         if (type == 1) { float* ko = kvo + (size_t)(ai * HALF + m * 16) * 512 + cl + 32 * bj; *(f32x4*)ko = a; *(f32x4*)(ko + 4) = b; }
;                         *(u32x4*)(QB + (size_t)type * BSTRIDE + (size_t)row * 512 + cl + 32 * bj) = pack8(a * sc, b * sc);
.LBB0_311:
	v_pk_mul_f32 v[124:125], v[112:113], v[112:113]
	v_pk_mul_f32 v[126:127], v[110:111], v[110:111]
	v_mov_b32_e32 v149, v148
	v_pk_mov_b32 v[128:129], v[126:127], v[124:125] op_sel:[1,0]
	v_mov_b32_e32 v127, v125
	v_pk_add_f32 v[124:125], v[128:129], v[126:127]
	v_pk_mul_f32 v[126:127], v[108:109], v[108:109]
	v_pk_mul_f32 v[128:129], v[106:107], v[106:107]
	v_pk_add_f32 v[124:125], v[124:125], v[124:125] op_sel:[0,1] op_sel_hi:[1,0]
	v_pk_mov_b32 v[150:151], v[128:129], v[126:127] op_sel:[1,0]
	v_mov_b32_e32 v129, v127
	v_pk_add_f32 v[126:127], v[150:151], v[128:129]
	v_mul_f32_e32 v128, v98, v98
	v_mul_f32_e32 v129, v99, v99
	v_pk_add_f32 v[126:127], v[126:127], v[126:127] op_sel:[0,1] op_sel_hi:[1,0]
	v_mov_b32_e32 v125, v128
	v_mov_b32_e32 v127, v129
	v_pk_add_f32 v[124:125], v[124:125], v[126:127]
	v_mul_f32_e32 v126, v103, v103
	v_mul_f32_e32 v128, v105, v105
	v_mul_f32_e32 v150, v100, v100
	v_mul_f32_e32 v151, v101, v101
	v_pk_fma_f32 v[126:127], v[102:103], v[102:103], v[126:127] op_sel_hi:[1,1,0]
	v_pk_fma_f32 v[128:129], v[104:105], v[104:105], v[128:129] op_sel_hi:[1,1,0]
	v_mov_b32_e32 v127, v150
	v_mov_b32_e32 v129, v151
	v_pk_add_f32 v[126:127], v[126:127], v[128:129]
	v_pk_mul_f32 v[118:119], v[148:149], v[118:119]
	v_pk_add_f32 v[124:125], v[124:125], v[126:127]
	s_nop 0
	v_add_f32_e32 v126, v124, v125
	v_mov_b32_e32 v127, v126
	s_nop 1
	v_permlane16_swap_b32_e32 v127, v126
	v_mov_b32_e32 v124, v148
	v_mov_b32_e32 v125, v148
	v_pk_mul_f32 v[120:121], v[124:125], v[120:121]
	s_waitcnt lgkmcnt(0)
	v_add_f32_e32 v128, v126, v127
	v_mov_b32_e32 v129, v128
	s_nop 1
	v_permlane32_swap_b32_e32 v129, v128
	v_pk_mul_f32 v[126:127], v[124:125], v[116:117]
	v_pk_mul_f32 v[116:117], v[148:149], v[114:115]
	v_cvt_pk_bf16_f32 v114, v118, v119
	v_cvt_pk_bf16_f32 v115, v120, v121
	s_waitcnt lgkmcnt(0)
	v_add_f32_e32 v118, v128, v129
	v_fmamk_f32 v118, v118, 0x3c800000, v195
	v_mul_f32_e32 v119, 0x4b800000, v118
	v_cmp_gt_f32_e32 vcc, s93, v118
	v_cvt_pk_bf16_f32 v116, v116, v117
	v_cvt_pk_bf16_f32 v117, v126, v127
	v_cndmask_b32_e32 v118, v118, v119, vcc
	v_rsq_f32_e32 v118, v118
	global_store_dwordx4 v[122:123], v[114:117], off offset:64
	s_nop 1
	v_mul_f32_e32 v114, 0x45800000, v118
	v_cndmask_b32_e32 v114, v118, v114, vcc
	v_pk_mul_f32 v[110:111], v[110:111], v[114:115] op_sel_hi:[1,0]
	v_pk_mul_f32 v[112:113], v[112:113], v[114:115] op_sel_hi:[1,0]
	v_pk_mul_f32 v[106:107], v[106:107], v[114:115] op_sel_hi:[1,0]
	v_pk_mul_f32 v[108:109], v[108:109], v[114:115] op_sel_hi:[1,0]
	v_pk_mul_f32 v[112:113], v[144:145], v[112:113]
	v_pk_mul_f32 v[110:111], v[142:143], v[110:111]
	v_pk_mul_f32 v[108:109], v[140:141], v[108:109]
	s_and_b64 vcc, exec, s[10:11]
	v_pk_mul_f32 v[106:107], v[138:139], v[106:107]
	s_cbranch_vccnz .LBB0_313
	v_add_co_u32_e32 v116, vcc, 0x8000, v146
	s_nop 1
	v_addc_co_u32_e32 v117, vcc, 0, v147, vcc
	global_store_dwordx4 v[116:117], v[110:113], off
	global_store_dwordx4 v[116:117], v[106:109], off offset:16

; __device__ __forceinline__ float dot4(f32x4 a) { return (a[0] * a[0] + a[1] * a[1]) + (a[2] * a[2] + a[3] * a[3]); }
; __device__ __forceinline__ u32x4 pack8(f32x4 a, f32x4 b) { u32x4 w; w.x = cvt_pk_bf16(a[0], a[1]); w.y = cvt_pk_bf16(a[2], a[3]); w.z = cvt_pk_bf16(b[0], b[1]); w.w = cvt_pk_bf16(b[2], b[3]); return w; }
;     __device__ __forceinline__ void operator()(const f32x4 (&acc)[2][2][4][2], const Unit& u, int wr, int wc, int fr, int fq) const {
;     ...
;                     const int row = row0 + ai * HALF + m * 16; f32x4 v[2][2]; float ss = 0.f;
; #pragma unroll
;                     for (int bj = 0; bj < 2; ++bj)
; #pragma unroll
;                         for (int n = 0; n < 2; ++n) { v[bj][n] = acc[ai][bj][m][n]; ss += dot4(v[bj][n]); }
;                     ss += __shfl_xor(ss, 16); ss += __shfl_xor(ss, 32);
;                     const float rn = rsqrtf(ss * (1.0f / 64.0f) + EPS);
; #pragma unroll
;                     for (int bj = 0; bj < 2; ++bj) {
;                         const f32x4 a = v[bj][0] * rn * gv[bj][0], b = v[bj][1] * rn * gv[bj][1];
;                         if (type == 1) { float* ko = kvo + (size_t)(ai * HALF + m * 16) * 512 + cl + 32 * bj; *(f32x4*)ko = a; *(f32x4*)(ko + 4) = b; }
;                         *(u32x4*)(QB + (size_t)type * BSTRIDE + (size_t)row * 512 + cl + 32 * bj) = pack8(a * sc, b * sc);
.LBB0_315:
	v_pk_mul_f32 v[108:109], v[96:97], v[96:97]
	v_pk_mul_f32 v[110:111], v[94:95], v[94:95]
	v_pk_mul_f32 v[102:103], v[148:149], v[102:103]
	v_pk_mov_b32 v[112:113], v[110:111], v[108:109] op_sel:[1,0]
	v_mov_b32_e32 v111, v109
	v_pk_add_f32 v[108:109], v[112:113], v[110:111]
	v_pk_mul_f32 v[110:111], v[92:93], v[92:93]
	v_pk_mul_f32 v[112:113], v[90:91], v[90:91]
	v_pk_add_f32 v[108:109], v[108:109], v[108:109] op_sel:[0,1] op_sel_hi:[1,0]
	v_pk_mov_b32 v[114:115], v[112:113], v[110:111] op_sel:[1,0]
	v_mov_b32_e32 v113, v111
	v_pk_add_f32 v[110:111], v[114:115], v[112:113]
	v_mul_f32_e32 v112, v82, v82
	v_mul_f32_e32 v113, v83, v83
	v_pk_add_f32 v[110:111], v[110:111], v[110:111] op_sel:[0,1] op_sel_hi:[1,0]
	v_mov_b32_e32 v109, v112
	v_mov_b32_e32 v111, v113
	v_pk_add_f32 v[108:109], v[108:109], v[110:111]
	v_mul_f32_e32 v110, v87, v87
	v_mul_f32_e32 v112, v89, v89
	v_mul_f32_e32 v114, v84, v84
	v_mul_f32_e32 v115, v85, v85
	v_pk_fma_f32 v[110:111], v[86:87], v[86:87], v[110:111] op_sel_hi:[1,1,0]
	v_pk_fma_f32 v[112:113], v[88:89], v[88:89], v[112:113] op_sel_hi:[1,1,0]
	v_mov_b32_e32 v111, v114
	v_mov_b32_e32 v113, v115
	v_pk_add_f32 v[110:111], v[110:111], v[112:113]
	s_nop 0
	v_pk_add_f32 v[108:109], v[108:109], v[110:111]
	s_nop 0
	v_add_f32_e32 v110, v108, v109
	v_mov_b32_e32 v111, v110
	s_nop 1
	v_permlane16_swap_b32_e32 v111, v110
	v_mov_b32_e32 v108, v148
	v_mov_b32_e32 v109, v148
	v_pk_mul_f32 v[104:105], v[108:109], v[104:105]
	s_waitcnt lgkmcnt(0)
	v_add_f32_e32 v112, v110, v111
	v_mov_b32_e32 v113, v112
	s_nop 1
	v_permlane32_swap_b32_e32 v113, v112
	v_pk_mul_f32 v[110:111], v[108:109], v[100:101]
	v_pk_mul_f32 v[100:101], v[148:149], v[98:99]
	v_cvt_pk_bf16_f32 v98, v102, v103
	v_cvt_pk_bf16_f32 v99, v104, v105
	s_waitcnt lgkmcnt(0)
	v_add_f32_e32 v102, v112, v113
	v_fmamk_f32 v102, v102, 0x3c800000, v195
	v_mul_f32_e32 v103, 0x4b800000, v102
	v_cmp_gt_f32_e32 vcc, s93, v102
	v_cvt_pk_bf16_f32 v100, v100, v101
	v_cvt_pk_bf16_f32 v101, v110, v111
	v_cndmask_b32_e32 v102, v102, v103, vcc
	v_rsq_f32_e32 v102, v102
	global_store_dwordx4 v[106:107], v[98:101], off offset:64
	s_nop 1
	v_mul_f32_e32 v98, 0x45800000, v102
	v_cndmask_b32_e32 v98, v102, v98, vcc
	v_pk_mul_f32 v[94:95], v[94:95], v[98:99] op_sel_hi:[1,0]
	v_pk_mul_f32 v[96:97], v[96:97], v[98:99] op_sel_hi:[1,0]
	v_pk_mul_f32 v[90:91], v[90:91], v[98:99] op_sel_hi:[1,0]
	v_pk_mul_f32 v[92:93], v[92:93], v[98:99] op_sel_hi:[1,0]
	v_pk_mul_f32 v[96:97], v[144:145], v[96:97]
	v_pk_mul_f32 v[94:95], v[142:143], v[94:95]
	v_pk_mul_f32 v[92:93], v[140:141], v[92:93]
	s_and_b64 vcc, exec, s[10:11]
	v_pk_mul_f32 v[90:91], v[138:139], v[90:91]
	s_cbranch_vccnz .LBB0_317
	v_add_co_u32_e32 v100, vcc, 0x10000, v146
	s_nop 1
	v_addc_co_u32_e32 v101, vcc, 0, v147, vcc
	global_store_dwordx4 v[100:101], v[94:97], off
	global_store_dwordx4 v[100:101], v[90:93], off offset:16

; __device__ __forceinline__ float dot4(f32x4 a) { return (a[0] * a[0] + a[1] * a[1]) + (a[2] * a[2] + a[3] * a[3]); }
; __device__ __forceinline__ u32x4 pack8(f32x4 a, f32x4 b) { u32x4 w; w.x = cvt_pk_bf16(a[0], a[1]); w.y = cvt_pk_bf16(a[2], a[3]); w.z = cvt_pk_bf16(b[0], b[1]); w.w = cvt_pk_bf16(b[2], b[3]); return w; }
;     __device__ __forceinline__ void operator()(const f32x4 (&acc)[2][2][4][2], const Unit& u, int wr, int wc, int fr, int fq) const {
;     ...
;                     const int row = row0 + ai * HALF + m * 16; f32x4 v[2][2]; float ss = 0.f;
; #pragma unroll
;                     for (int bj = 0; bj < 2; ++bj)
; #pragma unroll
;                         for (int n = 0; n < 2; ++n) { v[bj][n] = acc[ai][bj][m][n]; ss += dot4(v[bj][n]); }
;                     ss += __shfl_xor(ss, 16); ss += __shfl_xor(ss, 32);
;                     const float rn = rsqrtf(ss * (1.0f / 64.0f) + EPS);
; #pragma unroll
;                     for (int bj = 0; bj < 2; ++bj) {
;                         const f32x4 a = v[bj][0] * rn * gv[bj][0], b = v[bj][1] * rn * gv[bj][1];
;                         if (type == 1) { float* ko = kvo + (size_t)(ai * HALF + m * 16) * 512 + cl + 32 * bj; *(f32x4*)ko = a; *(f32x4*)(ko + 4) = b; }
;                         *(u32x4*)(QB + (size_t)type * BSTRIDE + (size_t)row * 512 + cl + 32 * bj) = pack8(a * sc, b * sc);
.LBB0_319:
	v_pk_mul_f32 v[92:93], v[80:81], v[80:81]
	v_pk_mul_f32 v[94:95], v[78:79], v[78:79]
	v_pk_mul_f32 v[86:87], v[148:149], v[86:87]
	v_pk_mov_b32 v[96:97], v[94:95], v[92:93] op_sel:[1,0]
	v_mov_b32_e32 v95, v93
	v_pk_add_f32 v[92:93], v[96:97], v[94:95]
	v_pk_mul_f32 v[94:95], v[76:77], v[76:77]
	v_pk_mul_f32 v[96:97], v[74:75], v[74:75]
	v_pk_add_f32 v[92:93], v[92:93], v[92:93] op_sel:[0,1] op_sel_hi:[1,0]
	v_pk_mov_b32 v[98:99], v[96:97], v[94:95] op_sel:[1,0]
	v_mov_b32_e32 v97, v95
	v_pk_add_f32 v[94:95], v[98:99], v[96:97]
	v_mul_f32_e32 v96, v66, v66
	v_mul_f32_e32 v97, v67, v67
	v_pk_add_f32 v[94:95], v[94:95], v[94:95] op_sel:[0,1] op_sel_hi:[1,0]
	v_mov_b32_e32 v93, v96
	v_mov_b32_e32 v95, v97
	v_pk_add_f32 v[92:93], v[92:93], v[94:95]
	v_mul_f32_e32 v94, v71, v71
	v_mul_f32_e32 v96, v73, v73
	v_mul_f32_e32 v98, v68, v68
	v_mul_f32_e32 v99, v69, v69
	v_pk_fma_f32 v[94:95], v[70:71], v[70:71], v[94:95] op_sel_hi:[1,1,0]
	v_pk_fma_f32 v[96:97], v[72:73], v[72:73], v[96:97] op_sel_hi:[1,1,0]
	v_mov_b32_e32 v95, v98
	v_mov_b32_e32 v97, v99
	v_pk_add_f32 v[94:95], v[94:95], v[96:97]
	s_nop 0
	v_pk_add_f32 v[92:93], v[92:93], v[94:95]
	s_nop 0
	v_add_f32_e32 v94, v92, v93
	v_mov_b32_e32 v95, v94
	s_nop 1
	v_permlane16_swap_b32_e32 v95, v94
	v_mov_b32_e32 v92, v148
	v_mov_b32_e32 v93, v148
	v_pk_mul_f32 v[88:89], v[92:93], v[88:89]
	s_waitcnt lgkmcnt(0)
	v_add_f32_e32 v96, v94, v95
	v_mov_b32_e32 v97, v96
	s_nop 1
	v_permlane32_swap_b32_e32 v97, v96
	v_pk_mul_f32 v[94:95], v[92:93], v[84:85]
	v_pk_mul_f32 v[84:85], v[148:149], v[82:83]
	v_cvt_pk_bf16_f32 v82, v86, v87
	v_cvt_pk_bf16_f32 v83, v88, v89
	s_waitcnt lgkmcnt(0)
	v_add_f32_e32 v86, v96, v97
	v_fmamk_f32 v86, v86, 0x3c800000, v195
	v_mul_f32_e32 v87, 0x4b800000, v86
	v_cmp_gt_f32_e32 vcc, s93, v86
	v_cvt_pk_bf16_f32 v84, v84, v85
	v_cvt_pk_bf16_f32 v85, v94, v95
	v_cndmask_b32_e32 v86, v86, v87, vcc
	v_rsq_f32_e32 v86, v86
	global_store_dwordx4 v[90:91], v[82:85], off offset:64
	s_nop 1
	v_mul_f32_e32 v82, 0x45800000, v86
	v_cndmask_b32_e32 v82, v86, v82, vcc
	v_pk_mul_f32 v[78:79], v[78:79], v[82:83] op_sel_hi:[1,0]
	v_pk_mul_f32 v[80:81], v[80:81], v[82:83] op_sel_hi:[1,0]
	v_pk_mul_f32 v[74:75], v[74:75], v[82:83] op_sel_hi:[1,0]
	v_pk_mul_f32 v[76:77], v[76:77], v[82:83] op_sel_hi:[1,0]
	v_pk_mul_f32 v[80:81], v[144:145], v[80:81]
	v_pk_mul_f32 v[78:79], v[142:143], v[78:79]
	v_pk_mul_f32 v[76:77], v[140:141], v[76:77]
	s_and_b64 vcc, exec, s[10:11]
	v_pk_mul_f32 v[74:75], v[138:139], v[74:75]
	s_cbranch_vccnz .LBB0_321
	v_add_co_u32_e32 v84, vcc, 0x18000, v146
	s_nop 1
	v_addc_co_u32_e32 v85, vcc, 0, v147, vcc
	global_store_dwordx4 v[84:85], v[78:81], off
	global_store_dwordx4 v[84:85], v[74:77], off offset:16

; __device__ __forceinline__ float dot4(f32x4 a) { return (a[0] * a[0] + a[1] * a[1]) + (a[2] * a[2] + a[3] * a[3]); }
; __device__ __forceinline__ u32x4 pack8(f32x4 a, f32x4 b) { u32x4 w; w.x = cvt_pk_bf16(a[0], a[1]); w.y = cvt_pk_bf16(a[2], a[3]); w.z = cvt_pk_bf16(b[0], b[1]); w.w = cvt_pk_bf16(b[2], b[3]); return w; }
;     __device__ __forceinline__ void operator()(const f32x4 (&acc)[2][2][4][2], const Unit& u, int wr, int wc, int fr, int fq) const {
;     ...
;                     const int row = row0 + ai * HALF + m * 16; f32x4 v[2][2]; float ss = 0.f;
; #pragma unroll
;                     for (int bj = 0; bj < 2; ++bj)
; #pragma unroll
;                         for (int n = 0; n < 2; ++n) { v[bj][n] = acc[ai][bj][m][n]; ss += dot4(v[bj][n]); }
;                     ss += __shfl_xor(ss, 16); ss += __shfl_xor(ss, 32);
;                     const float rn = rsqrtf(ss * (1.0f / 64.0f) + EPS);
; #pragma unroll
;                     for (int bj = 0; bj < 2; ++bj) {
;                         const f32x4 a = v[bj][0] * rn * gv[bj][0], b = v[bj][1] * rn * gv[bj][1];
;                         if (type == 1) { float* ko = kvo + (size_t)(ai * HALF + m * 16) * 512 + cl + 32 * bj; *(f32x4*)ko = a; *(f32x4*)(ko + 4) = b; }
;                         *(u32x4*)(QB + (size_t)type * BSTRIDE + (size_t)row * 512 + cl + 32 * bj) = pack8(a * sc, b * sc);
.LBB0_323:
	v_pk_mul_f32 v[76:77], v[64:65], v[64:65]
	v_pk_mul_f32 v[78:79], v[62:63], v[62:63]
	v_pk_mul_f32 v[70:71], v[148:149], v[70:71]
	v_pk_mov_b32 v[80:81], v[78:79], v[76:77] op_sel:[1,0]
	v_mov_b32_e32 v79, v77
	v_pk_add_f32 v[76:77], v[80:81], v[78:79]
	v_pk_mul_f32 v[78:79], v[60:61], v[60:61]
	v_pk_mul_f32 v[80:81], v[58:59], v[58:59]
	v_pk_add_f32 v[76:77], v[76:77], v[76:77] op_sel:[0,1] op_sel_hi:[1,0]
	v_pk_mov_b32 v[82:83], v[80:81], v[78:79] op_sel:[1,0]
	v_mov_b32_e32 v81, v79
	v_pk_add_f32 v[78:79], v[82:83], v[80:81]
	v_mul_f32_e32 v80, v50, v50
	v_mul_f32_e32 v81, v51, v51
	v_pk_add_f32 v[78:79], v[78:79], v[78:79] op_sel:[0,1] op_sel_hi:[1,0]
	v_mov_b32_e32 v77, v80
	v_mov_b32_e32 v79, v81
	v_pk_add_f32 v[76:77], v[76:77], v[78:79]
	v_mul_f32_e32 v78, v55, v55
	v_mul_f32_e32 v80, v57, v57
	v_mul_f32_e32 v82, v52, v52
	v_mul_f32_e32 v83, v53, v53
	v_pk_fma_f32 v[78:79], v[54:55], v[54:55], v[78:79] op_sel_hi:[1,1,0]
	v_pk_fma_f32 v[80:81], v[56:57], v[56:57], v[80:81] op_sel_hi:[1,1,0]
	v_mov_b32_e32 v79, v82
	v_mov_b32_e32 v81, v83
	v_pk_add_f32 v[78:79], v[78:79], v[80:81]
	s_nop 0
	v_pk_add_f32 v[76:77], v[76:77], v[78:79]
	s_nop 0
	v_add_f32_e32 v78, v76, v77
	v_mov_b32_e32 v79, v78
	s_nop 1
	v_permlane16_swap_b32_e32 v79, v78
	v_mov_b32_e32 v76, v148
	v_mov_b32_e32 v77, v148
	v_pk_mul_f32 v[72:73], v[76:77], v[72:73]
	s_waitcnt lgkmcnt(0)
	v_add_f32_e32 v80, v78, v79
	v_mov_b32_e32 v81, v80
	s_nop 1
	v_permlane32_swap_b32_e32 v81, v80
	v_pk_mul_f32 v[78:79], v[76:77], v[68:69]
	v_pk_mul_f32 v[68:69], v[148:149], v[66:67]
	v_cvt_pk_bf16_f32 v66, v70, v71
	v_cvt_pk_bf16_f32 v67, v72, v73
	s_waitcnt lgkmcnt(0)
	v_add_f32_e32 v70, v80, v81
	v_fmamk_f32 v70, v70, 0x3c800000, v195
	v_mul_f32_e32 v71, 0x4b800000, v70
	v_cmp_gt_f32_e32 vcc, s93, v70
	v_cvt_pk_bf16_f32 v68, v68, v69
	v_cvt_pk_bf16_f32 v69, v78, v79
	v_cndmask_b32_e32 v70, v70, v71, vcc
	v_rsq_f32_e32 v70, v70
	global_store_dwordx4 v[74:75], v[66:69], off offset:64
	s_nop 1
	v_mul_f32_e32 v66, 0x45800000, v70
	v_cndmask_b32_e32 v66, v70, v66, vcc
	v_pk_mul_f32 v[62:63], v[62:63], v[66:67] op_sel_hi:[1,0]
	v_pk_mul_f32 v[64:65], v[64:65], v[66:67] op_sel_hi:[1,0]
	v_pk_mul_f32 v[58:59], v[58:59], v[66:67] op_sel_hi:[1,0]
	v_pk_mul_f32 v[60:61], v[60:61], v[66:67] op_sel_hi:[1,0]
	v_pk_mul_f32 v[64:65], v[144:145], v[64:65]
	v_pk_mul_f32 v[62:63], v[142:143], v[62:63]
	v_pk_mul_f32 v[60:61], v[140:141], v[60:61]
	s_and_b64 vcc, exec, s[10:11]
	v_pk_mul_f32 v[58:59], v[138:139], v[58:59]
	s_cbranch_vccnz .LBB0_325
	v_add_co_u32_e32 v68, vcc, 0x40000, v146
	s_nop 1
	v_addc_co_u32_e32 v69, vcc, 0, v147, vcc
	global_store_dwordx4 v[68:69], v[62:65], off
	global_store_dwordx4 v[68:69], v[58:61], off offset:16

; __device__ __forceinline__ float dot4(f32x4 a) { return (a[0] * a[0] + a[1] * a[1]) + (a[2] * a[2] + a[3] * a[3]); }
; __device__ __forceinline__ u32x4 pack8(f32x4 a, f32x4 b) { u32x4 w; w.x = cvt_pk_bf16(a[0], a[1]); w.y = cvt_pk_bf16(a[2], a[3]); w.z = cvt_pk_bf16(b[0], b[1]); w.w = cvt_pk_bf16(b[2], b[3]); return w; }
;     __device__ __forceinline__ void operator()(const f32x4 (&acc)[2][2][4][2], const Unit& u, int wr, int wc, int fr, int fq) const {
;     ...
;                     const int row = row0 + ai * HALF + m * 16; f32x4 v[2][2]; float ss = 0.f;
; #pragma unroll
;                     for (int bj = 0; bj < 2; ++bj)
; #pragma unroll
;                         for (int n = 0; n < 2; ++n) { v[bj][n] = acc[ai][bj][m][n]; ss += dot4(v[bj][n]); }
;                     ss += __shfl_xor(ss, 16); ss += __shfl_xor(ss, 32);
;                     const float rn = rsqrtf(ss * (1.0f / 64.0f) + EPS);
; #pragma unroll
;                     for (int bj = 0; bj < 2; ++bj) {
;                         const f32x4 a = v[bj][0] * rn * gv[bj][0], b = v[bj][1] * rn * gv[bj][1];
;                         if (type == 1) { float* ko = kvo + (size_t)(ai * HALF + m * 16) * 512 + cl + 32 * bj; *(f32x4*)ko = a; *(f32x4*)(ko + 4) = b; }
;                         *(u32x4*)(QB + (size_t)type * BSTRIDE + (size_t)row * 512 + cl + 32 * bj) = pack8(a * sc, b * sc);
.LBB0_327:
	v_lshl_add_u64 v[60:61], v[58:59], 0, s[34:35]
	v_pk_mul_f32 v[58:59], v[48:49], v[48:49]
	v_pk_mul_f32 v[62:63], v[46:47], v[46:47]
	v_pk_mul_f32 v[54:55], v[148:149], v[54:55]
	v_pk_mov_b32 v[64:65], v[62:63], v[58:59] op_sel:[1,0]
	v_mov_b32_e32 v63, v59
	v_pk_add_f32 v[58:59], v[64:65], v[62:63]
	v_pk_mul_f32 v[62:63], v[44:45], v[44:45]
	v_pk_mul_f32 v[64:65], v[42:43], v[42:43]
	v_pk_add_f32 v[58:59], v[58:59], v[58:59] op_sel:[0,1] op_sel_hi:[1,0]
	v_pk_mov_b32 v[66:67], v[64:65], v[62:63] op_sel:[1,0]
	v_mov_b32_e32 v65, v63
	v_pk_add_f32 v[62:63], v[66:67], v[64:65]
	v_mul_f32_e32 v64, v34, v34
	v_mul_f32_e32 v65, v35, v35
	v_pk_add_f32 v[62:63], v[62:63], v[62:63] op_sel:[0,1] op_sel_hi:[1,0]
	v_mov_b32_e32 v59, v64
	v_mov_b32_e32 v63, v65
	v_pk_add_f32 v[58:59], v[58:59], v[62:63]
	v_mul_f32_e32 v62, v39, v39
	v_mul_f32_e32 v64, v41, v41
	v_mul_f32_e32 v66, v36, v36
	v_mul_f32_e32 v67, v37, v37
	v_pk_fma_f32 v[62:63], v[38:39], v[38:39], v[62:63] op_sel_hi:[1,1,0]
	v_pk_fma_f32 v[64:65], v[40:41], v[40:41], v[64:65] op_sel_hi:[1,1,0]
	v_mov_b32_e32 v63, v66
	v_mov_b32_e32 v65, v67
	v_pk_add_f32 v[62:63], v[62:63], v[64:65]
	s_nop 0
	v_pk_add_f32 v[58:59], v[58:59], v[62:63]
	s_nop 0
	v_add_f32_e32 v62, v58, v59
	v_mov_b32_e32 v63, v62
	s_nop 1
	v_permlane16_swap_b32_e32 v63, v62
	v_mov_b32_e32 v58, v148
	v_mov_b32_e32 v59, v148
	v_pk_mul_f32 v[56:57], v[58:59], v[56:57]
	s_waitcnt lgkmcnt(0)
	v_add_f32_e32 v64, v62, v63
	v_mov_b32_e32 v65, v64
	s_nop 1
	v_permlane32_swap_b32_e32 v65, v64
	v_pk_mul_f32 v[62:63], v[58:59], v[52:53]
	v_pk_mul_f32 v[52:53], v[148:149], v[50:51]
	v_cvt_pk_bf16_f32 v50, v54, v55
	v_cvt_pk_bf16_f32 v51, v56, v57
	s_waitcnt lgkmcnt(0)
	v_add_f32_e32 v54, v64, v65
	v_fmamk_f32 v54, v54, 0x3c800000, v195
	v_mul_f32_e32 v55, 0x4b800000, v54
	v_cmp_gt_f32_e32 vcc, s93, v54
	v_cvt_pk_bf16_f32 v52, v52, v53
	v_cvt_pk_bf16_f32 v53, v62, v63
	v_cndmask_b32_e32 v54, v54, v55, vcc
	v_rsq_f32_e32 v54, v54
	global_store_dwordx4 v[60:61], v[50:53], off offset:64
	s_nop 1
	v_mul_f32_e32 v50, 0x45800000, v54
	v_cndmask_b32_e32 v50, v54, v50, vcc
	v_pk_mul_f32 v[46:47], v[46:47], v[50:51] op_sel_hi:[1,0]
	v_pk_mul_f32 v[48:49], v[48:49], v[50:51] op_sel_hi:[1,0]
	v_pk_mul_f32 v[42:43], v[42:43], v[50:51] op_sel_hi:[1,0]
	v_pk_mul_f32 v[44:45], v[44:45], v[50:51] op_sel_hi:[1,0]
	v_pk_mul_f32 v[48:49], v[144:145], v[48:49]
	v_pk_mul_f32 v[46:47], v[142:143], v[46:47]
	v_pk_mul_f32 v[44:45], v[140:141], v[44:45]
	s_and_b64 vcc, exec, s[10:11]
	v_pk_mul_f32 v[42:43], v[138:139], v[42:43]
	s_cbranch_vccnz .LBB0_329
	v_add_co_u32_e32 v52, vcc, 0x48000, v146
	s_nop 1
	v_addc_co_u32_e32 v53, vcc, 0, v147, vcc
	global_store_dwordx4 v[52:53], v[46:49], off
	global_store_dwordx4 v[52:53], v[42:45], off offset:16

; __device__ __forceinline__ float dot4(f32x4 a) { return (a[0] * a[0] + a[1] * a[1]) + (a[2] * a[2] + a[3] * a[3]); }
; __device__ __forceinline__ u32x4 pack8(f32x4 a, f32x4 b) { u32x4 w; w.x = cvt_pk_bf16(a[0], a[1]); w.y = cvt_pk_bf16(a[2], a[3]); w.z = cvt_pk_bf16(b[0], b[1]); w.w = cvt_pk_bf16(b[2], b[3]); return w; }
;     __device__ __forceinline__ void operator()(const f32x4 (&acc)[2][2][4][2], const Unit& u, int wr, int wc, int fr, int fq) const {
;     ...
;                     const int row = row0 + ai * HALF + m * 16; f32x4 v[2][2]; float ss = 0.f;
; #pragma unroll
;                     for (int bj = 0; bj < 2; ++bj)
; #pragma unroll
;                         for (int n = 0; n < 2; ++n) { v[bj][n] = acc[ai][bj][m][n]; ss += dot4(v[bj][n]); }
;                     ss += __shfl_xor(ss, 16); ss += __shfl_xor(ss, 32);
;                     const float rn = rsqrtf(ss * (1.0f / 64.0f) + EPS);
; #pragma unroll
;                     for (int bj = 0; bj < 2; ++bj) {
;                         const f32x4 a = v[bj][0] * rn * gv[bj][0], b = v[bj][1] * rn * gv[bj][1];
;                         if (type == 1) { float* ko = kvo + (size_t)(ai * HALF + m * 16) * 512 + cl + 32 * bj; *(f32x4*)ko = a; *(f32x4*)(ko + 4) = b; }
;                         *(u32x4*)(QB + (size_t)type * BSTRIDE + (size_t)row * 512 + cl + 32 * bj) = pack8(a * sc, b * sc);
;                     }
.LBB0_331:
	v_lshl_add_u64 v[44:45], v[42:43], 0, s[36:37]
	v_pk_mul_f32 v[42:43], v[32:33], v[32:33]
	v_pk_mul_f32 v[46:47], v[30:31], v[30:31]
	v_pk_mul_f32 v[38:39], v[148:149], v[38:39]
	v_pk_mov_b32 v[48:49], v[46:47], v[42:43] op_sel:[1,0]
	v_mov_b32_e32 v47, v43
	v_pk_add_f32 v[42:43], v[48:49], v[46:47]
	v_pk_mul_f32 v[46:47], v[28:29], v[28:29]
	v_pk_mul_f32 v[48:49], v[26:27], v[26:27]
	v_pk_add_f32 v[42:43], v[42:43], v[42:43] op_sel:[0,1] op_sel_hi:[1,0]
	v_pk_mov_b32 v[50:51], v[48:49], v[46:47] op_sel:[1,0]
	v_mov_b32_e32 v49, v47
	v_pk_add_f32 v[46:47], v[50:51], v[48:49]
	v_mul_f32_e32 v48, v18, v18
	v_mul_f32_e32 v49, v19, v19
	v_pk_add_f32 v[46:47], v[46:47], v[46:47] op_sel:[0,1] op_sel_hi:[1,0]
	v_mov_b32_e32 v43, v48
	v_mov_b32_e32 v47, v49
	v_pk_add_f32 v[42:43], v[42:43], v[46:47]
	v_mul_f32_e32 v46, v23, v23
	v_mul_f32_e32 v48, v25, v25
	v_mul_f32_e32 v50, v20, v20
	v_mul_f32_e32 v51, v21, v21
	v_pk_fma_f32 v[46:47], v[22:23], v[22:23], v[46:47] op_sel_hi:[1,1,0]
	v_pk_fma_f32 v[48:49], v[24:25], v[24:25], v[48:49] op_sel_hi:[1,1,0]
	v_mov_b32_e32 v47, v50
	v_mov_b32_e32 v49, v51
	v_pk_add_f32 v[46:47], v[46:47], v[48:49]
	s_nop 0
	v_pk_add_f32 v[42:43], v[42:43], v[46:47]
	s_nop 0
	v_add_f32_e32 v46, v42, v43
	v_mov_b32_e32 v47, v46
	s_nop 1
	v_permlane16_swap_b32_e32 v47, v46
	v_mov_b32_e32 v42, v148
	v_mov_b32_e32 v43, v148
	v_pk_mul_f32 v[40:41], v[42:43], v[40:41]
	s_waitcnt lgkmcnt(0)
	v_add_f32_e32 v48, v46, v47
	v_mov_b32_e32 v49, v48
	s_nop 1
	v_permlane32_swap_b32_e32 v49, v48
	v_pk_mul_f32 v[46:47], v[42:43], v[36:37]
	v_pk_mul_f32 v[36:37], v[148:149], v[34:35]
	v_cvt_pk_bf16_f32 v34, v38, v39
	v_cvt_pk_bf16_f32 v35, v40, v41
	s_waitcnt lgkmcnt(0)
	v_add_f32_e32 v38, v48, v49
	v_fmamk_f32 v38, v38, 0x3c800000, v195
	v_mul_f32_e32 v39, 0x4b800000, v38
	v_cmp_gt_f32_e32 vcc, s93, v38
	v_cvt_pk_bf16_f32 v36, v36, v37
	v_cvt_pk_bf16_f32 v37, v46, v47
	v_cndmask_b32_e32 v38, v38, v39, vcc
	v_rsq_f32_e32 v38, v38
	global_store_dwordx4 v[44:45], v[34:37], off offset:64
	s_nop 1
	v_mul_f32_e32 v34, 0x45800000, v38
	v_cndmask_b32_e32 v34, v38, v34, vcc
	v_pk_mul_f32 v[30:31], v[30:31], v[34:35] op_sel_hi:[1,0]
	v_pk_mul_f32 v[32:33], v[32:33], v[34:35] op_sel_hi:[1,0]
	v_pk_mul_f32 v[26:27], v[26:27], v[34:35] op_sel_hi:[1,0]
	v_pk_mul_f32 v[28:29], v[28:29], v[34:35] op_sel_hi:[1,0]
	v_pk_mul_f32 v[32:33], v[144:145], v[32:33]
	v_pk_mul_f32 v[30:31], v[142:143], v[30:31]
	v_pk_mul_f32 v[28:29], v[140:141], v[28:29]
	s_and_b64 vcc, exec, s[10:11]
	v_pk_mul_f32 v[26:27], v[138:139], v[26:27]
	s_cbranch_vccnz .LBB0_333
	v_add_co_u32_e32 v36, vcc, 0x50000, v146
	s_nop 1
	v_addc_co_u32_e32 v37, vcc, 0, v147, vcc
	global_store_dwordx4 v[36:37], v[30:33], off
	global_store_dwordx4 v[36:37], v[26:29], off offset:16

; __device__ __forceinline__ float dot4(f32x4 a) { return (a[0] * a[0] + a[1] * a[1]) + (a[2] * a[2] + a[3] * a[3]); }
; __device__ __forceinline__ u32x4 pack8(f32x4 a, f32x4 b) { u32x4 w; w.x = cvt_pk_bf16(a[0], a[1]); w.y = cvt_pk_bf16(a[2], a[3]); w.z = cvt_pk_bf16(b[0], b[1]); w.w = cvt_pk_bf16(b[2], b[3]); return w; }
;     __device__ __forceinline__ void operator()(const f32x4 (&acc)[2][2][4][2], const Unit& u, int wr, int wc, int fr, int fq) const {
;     ...
;                     const int row = row0 + ai * HALF + m * 16; f32x4 v[2][2]; float ss = 0.f;
; #pragma unroll
;                     for (int bj = 0; bj < 2; ++bj)
; #pragma unroll
;                         for (int n = 0; n < 2; ++n) { v[bj][n] = acc[ai][bj][m][n]; ss += dot4(v[bj][n]); }
;                     ss += __shfl_xor(ss, 16); ss += __shfl_xor(ss, 32);
;                     const float rn = rsqrtf(ss * (1.0f / 64.0f) + EPS);
; #pragma unroll
;                     for (int bj = 0; bj < 2; ++bj) {
;                         const f32x4 a = v[bj][0] * rn * gv[bj][0], b = v[bj][1] * rn * gv[bj][1];
;                         if (type == 1) { float* ko = kvo + (size_t)(ai * HALF + m * 16) * 512 + cl + 32 * bj; *(f32x4*)ko = a; *(f32x4*)(ko + 4) = b; }
;                         *(u32x4*)(QB + (size_t)type * BSTRIDE + (size_t)row * 512 + cl + 32 * bj) = pack8(a * sc, b * sc);
;                     }
.LBB0_335:
	v_lshl_add_u64 v[28:29], v[26:27], 0, s[38:39]
	v_pk_mul_f32 v[26:27], v[16:17], v[16:17]
	v_pk_mul_f32 v[30:31], v[14:15], v[14:15]
	v_pk_mul_f32 v[22:23], v[148:149], v[22:23]
	v_pk_mov_b32 v[32:33], v[30:31], v[26:27] op_sel:[1,0]
	v_mov_b32_e32 v31, v27
	v_pk_add_f32 v[26:27], v[32:33], v[30:31]
	v_pk_mul_f32 v[30:31], v[12:13], v[12:13]
	v_pk_mul_f32 v[32:33], v[10:11], v[10:11]
	v_pk_add_f32 v[26:27], v[26:27], v[26:27] op_sel:[0,1] op_sel_hi:[1,0]
	v_pk_mov_b32 v[34:35], v[32:33], v[30:31] op_sel:[1,0]
	v_mov_b32_e32 v33, v31
	v_pk_add_f32 v[30:31], v[34:35], v[32:33]
	v_mul_f32_e32 v32, v2, v2
	v_mul_f32_e32 v33, v3, v3
	v_pk_add_f32 v[30:31], v[30:31], v[30:31] op_sel:[0,1] op_sel_hi:[1,0]
	v_mov_b32_e32 v27, v32
	v_mov_b32_e32 v31, v33
	v_pk_add_f32 v[26:27], v[26:27], v[30:31]
	v_mul_f32_e32 v30, v7, v7
	v_mul_f32_e32 v32, v9, v9
	v_mul_f32_e32 v34, v4, v4
	v_mul_f32_e32 v35, v5, v5
	v_pk_fma_f32 v[30:31], v[6:7], v[6:7], v[30:31] op_sel_hi:[1,1,0]
	v_pk_fma_f32 v[32:33], v[8:9], v[8:9], v[32:33] op_sel_hi:[1,1,0]
	v_mov_b32_e32 v31, v34
	v_mov_b32_e32 v33, v35
	v_pk_add_f32 v[30:31], v[30:31], v[32:33]
	s_nop 0
	v_pk_add_f32 v[26:27], v[26:27], v[30:31]
	s_nop 0
	v_add_f32_e32 v30, v26, v27
	v_mov_b32_e32 v31, v30
	s_nop 1
	v_permlane16_swap_b32_e32 v31, v30
	v_mov_b32_e32 v26, v148
	v_mov_b32_e32 v27, v148
	v_pk_mul_f32 v[24:25], v[26:27], v[24:25]
	s_waitcnt lgkmcnt(0)
	v_add_f32_e32 v32, v30, v31
	v_mov_b32_e32 v33, v32
	s_nop 1
	v_permlane32_swap_b32_e32 v33, v32
	v_pk_mul_f32 v[30:31], v[26:27], v[20:21]
	v_pk_mul_f32 v[20:21], v[148:149], v[18:19]
	v_cvt_pk_bf16_f32 v18, v22, v23
	v_cvt_pk_bf16_f32 v19, v24, v25
	s_waitcnt lgkmcnt(0)
	v_add_f32_e32 v22, v32, v33
	v_fmamk_f32 v22, v22, 0x3c800000, v195
	v_mul_f32_e32 v23, 0x4b800000, v22
	v_cmp_gt_f32_e32 vcc, s93, v22
	v_cvt_pk_bf16_f32 v20, v20, v21
	v_cvt_pk_bf16_f32 v21, v30, v31
	v_cndmask_b32_e32 v22, v22, v23, vcc
	v_rsq_f32_e32 v22, v22
	global_store_dwordx4 v[28:29], v[18:21], off offset:64
	s_nop 1
	v_mul_f32_e32 v18, 0x45800000, v22
	v_cndmask_b32_e32 v18, v22, v18, vcc
	v_pk_mul_f32 v[14:15], v[14:15], v[18:19] op_sel_hi:[1,0]
	v_pk_mul_f32 v[16:17], v[16:17], v[18:19] op_sel_hi:[1,0]
	v_pk_mul_f32 v[10:11], v[10:11], v[18:19] op_sel_hi:[1,0]
	v_pk_mul_f32 v[12:13], v[12:13], v[18:19] op_sel_hi:[1,0]
	v_pk_mul_f32 v[16:17], v[144:145], v[16:17]
	v_pk_mul_f32 v[14:15], v[142:143], v[14:15]
	v_pk_mul_f32 v[12:13], v[140:141], v[12:13]
	s_and_b64 vcc, exec, s[10:11]
	v_pk_mul_f32 v[10:11], v[138:139], v[10:11]
	s_cbranch_vccnz .LBB0_337
	v_add_co_u32_e32 v20, vcc, 0x58000, v146
	s_nop 1
	v_addc_co_u32_e32 v21, vcc, 0, v147, vcc
	global_store_dwordx4 v[20:21], v[14:17], off
	global_store_dwordx4 v[20:21], v[10:13], off offset:16

; __device__ __forceinline__ float dot4(f32x4 a) { return (a[0] * a[0] + a[1] * a[1]) + (a[2] * a[2] + a[3] * a[3]); }
; __device__ __forceinline__ void store16_wt(void* p, u32x4 v) { asm volatile("global_store_dwordx4 %0, %1, off sc1\n\ts_nop 1" :: "v"(p), "v"(v) : "memory"); }
; __device__ __forceinline__ u32x4 pack8(f32x4 a, f32x4 b) { u32x4 w; w.x = cvt_pk_bf16(a[0], a[1]); w.y = cvt_pk_bf16(a[2], a[3]); w.z = cvt_pk_bf16(b[0], b[1]); w.w = cvt_pk_bf16(b[2], b[3]); return w; }
;     __device__ __forceinline__ void operator()(const f32x4 (&acc)[2][2][4][2], const Unit& u, int wr, int wc, int fr, int fq) const {
;         const int row0 = u.pm * BM + wr * 64 + fr, col0 = u.pn * BM + wc * 32 + 8 * fq;
; #pragma unroll
;         for (int ai = 0; ai < 2; ++ai) {
;             u32x4 xw[4][2]; float rms[4];
; #pragma unroll
;             for (int m = 0; m < 4; ++m) { const int row = row0 + ai * HALF + m * 16; rms[m] = rms1[row];
; #pragma unroll
;                 for (int bj = 0; bj < 2; ++bj) xw[m][bj] = *(const u32x4*)(XB + (size_t)row * 1024 + col0 + bj * HALF); }
; #pragma unroll
;             for (int m = 0; m < 4; ++m) {
;                 const int row = row0 + ai * HALF + m * 16;
;                 float ss = 0.f; const float r = rms[m];
; #pragma unroll
;                 for (int bj = 0; bj < 2; ++bj) { const int col = col0 + bj * HALF; const u32x4 w = xw[m][bj];
;                     const f32x4 a = (f32x4){__builtin_bit_cast(float, w.x << 16), __builtin_bit_cast(float, w.x & 0xffff0000u), __builtin_bit_cast(float, w.y << 16), __builtin_bit_cast(float, w.y & 0xffff0000u)} * r + acc[ai][bj][m][0],
;                                 b = (f32x4){__builtin_bit_cast(float, w.z << 16), __builtin_bit_cast(float, w.z & 0xffff0000u), __builtin_bit_cast(float, w.w << 16), __builtin_bit_cast(float, w.w & 0xffff0000u)} * r + acc[ai][bj][m][1];
;                     ss += dot4(a) + dot4(b);
;                     store16_wt(X1B + (size_t)row * 1024 + col, pack8(a, b)); }
;                 ss += __shfl_xor(ss, 16); ss += __shfl_xor(ss, 32);
;                 if (fq == 0) __hip_atomic_fetch_add(RSS + row, ss, __ATOMIC_RELAXED, __HIP_MEMORY_SCOPE_AGENT);
.LBB0_724:
	v_mbcnt_lo_u32_b32 v165, -1, 0
	v_mbcnt_hi_u32_b32 v165, -1, v165
	s_lshl_b32 s8, s8, 8
	v_ashrrev_i32_e32 v130, 1, v165
	s_lshl_b32 s9, s22, 8
	s_or_b32 s8, s8, s45
	v_and_b32_e32 v130, -8, v130
	s_add_i32 s9, s9, s44
	v_add_u32_e32 v154, s8, v130
	v_and_or_b32 v158, v165, 15, s9
	v_ashrrev_i32_e32 v155, 31, v154
	v_lshlrev_b64 v[188:189], 1, v[154:155]
	v_ashrrev_i32_e32 v159, 31, v158
	v_lshl_add_u64 v[156:157], s[16:17], 0, v[188:189]
	v_lshlrev_b64 v[190:191], 11, v[158:159]
	v_lshl_add_u64 v[130:131], v[156:157], 0, v[190:191]
	v_lshl_add_u64 v[160:161], v[158:159], 2, s[14:15]
	global_load_dwordx4 v[180:183], v[130:131], off
	global_load_dwordx4 v[184:187], v[130:131], off offset:256
	global_load_dword v192, v[160:161], off
	v_or_b32_e32 v174, 16, v158
	v_or_b32_e32 v168, 32, v158
	v_or_b32_e32 v162, 48, v158
	v_ashrrev_i32_e32 v175, 31, v174
	v_ashrrev_i32_e32 v169, 31, v168
	v_ashrrev_i32_e32 v163, 31, v162
	v_lshlrev_b64 v[178:179], 11, v[174:175]
	v_lshlrev_b64 v[172:173], 11, v[168:169]
	v_lshl_add_u64 v[130:131], v[174:175], 2, s[14:15]
	v_lshl_add_u64 v[132:133], v[168:169], 2, s[14:15]
	v_lshl_add_u64 v[134:135], v[162:163], 2, s[14:15]
	v_lshlrev_b64 v[166:167], 11, v[162:163]
	v_lshl_add_u64 v[136:137], v[156:157], 0, v[178:179]
	v_lshl_add_u64 v[138:139], v[156:157], 0, v[172:173]
	v_lshl_add_u64 v[194:195], v[156:157], 0, v[166:167]
	global_load_dword v176, v[130:131], off
	global_load_dwordx4 v[150:153], v[136:137], off
	global_load_dwordx4 v[146:149], v[136:137], off offset:256
	global_load_dword v170, v[132:133], off
	global_load_dwordx4 v[142:145], v[138:139], off
	s_nop 0
	global_load_dwordx4 v[138:141], v[138:139], off offset:256
	s_nop 0
	global_load_dword v164, v[134:135], off
	s_nop 0
	global_load_dwordx4 v[134:137], v[194:195], off
	global_load_dwordx4 v[130:133], v[194:195], off offset:256
	v_lshl_add_u64 v[190:191], s[12:13], 0, v[190:191]
	v_lshl_add_u64 v[188:189], v[190:191], 0, v[188:189]
	v_cmp_gt_u32_e32 vcc, 16, v165
	s_mov_b64 s[24:25], 0x100
	v_add_u32_e32 v250, 0x80, v158
	v_ashrrev_i32_e32 v251, 31, v250
	v_lshlrev_b64 v[252:253], 11, v[250:251]
	v_lshl_add_u64 v[246:247], v[156:157], 0, v[252:253]
	global_load_dwordx4 v[200:203], v[246:247], off
	global_load_dwordx4 v[204:207], v[246:247], off offset:256
	global_load_dword v236, v[160:161], off offset:512
	v_add_u32_e32 v250, 0x90, v158
	v_ashrrev_i32_e32 v251, 31, v250
	v_lshlrev_b64 v[252:253], 11, v[250:251]
	v_lshl_add_u64 v[246:247], v[156:157], 0, v[252:253]
	global_load_dwordx4 v[208:211], v[246:247], off
	global_load_dwordx4 v[212:215], v[246:247], off offset:256
	global_load_dword v238, v[160:161], off offset:576
	v_add_u32_e32 v250, 0xa0, v158
	v_ashrrev_i32_e32 v251, 31, v250
	v_lshlrev_b64 v[252:253], 11, v[250:251]
	v_lshl_add_u64 v[246:247], v[156:157], 0, v[252:253]
	global_load_dwordx4 v[216:219], v[246:247], off
	global_load_dwordx4 v[220:223], v[246:247], off offset:256
	global_load_dword v240, v[160:161], off offset:640
	v_add_u32_e32 v250, 0xb0, v158
	v_ashrrev_i32_e32 v251, 31, v250
	v_lshlrev_b64 v[252:253], 11, v[250:251]
	v_lshl_add_u64 v[246:247], v[156:157], 0, v[252:253]
	global_load_dwordx4 v[224:227], v[246:247], off
	global_load_dwordx4 v[232:235], v[246:247], off offset:256
	global_load_dword v244, v[160:161], off offset:704
	s_waitcnt vmcnt(0)
	v_lshlrev_b32_e32 v190, 16, v180
	v_and_b32_e32 v191, 0xffff0000, v180
	v_lshlrev_b32_e32 v180, 16, v181
	v_and_b32_e32 v181, 0xffff0000, v181
	v_lshlrev_b32_e32 v194, 16, v182
	v_and_b32_e32 v195, 0xffff0000, v182
	v_lshlrev_b32_e32 v182, 16, v183
	v_and_b32_e32 v183, 0xffff0000, v183
	v_lshlrev_b32_e32 v196, 16, v184
	v_and_b32_e32 v197, 0xffff0000, v184
	v_lshlrev_b32_e32 v184, 16, v185
	v_and_b32_e32 v185, 0xffff0000, v185
	v_lshlrev_b32_e32 v198, 16, v186
	v_and_b32_e32 v199, 0xffff0000, v186
	v_lshlrev_b32_e32 v186, 16, v187
	v_and_b32_e32 v187, 0xffff0000, v187
	v_pk_fma_f32 v[128:129], v[192:193], v[180:181], v[128:129] op_sel_hi:[0,1,1]
	v_pk_fma_f32 v[126:127], v[192:193], v[190:191], v[126:127] op_sel_hi:[0,1,1]
	v_pk_fma_f32 v[124:125], v[192:193], v[182:183], v[124:125] op_sel_hi:[0,1,1]
	v_pk_fma_f32 v[122:123], v[192:193], v[194:195], v[122:123] op_sel_hi:[0,1,1]
	v_pk_fma_f32 v[120:121], v[192:193], v[184:185], v[120:121] op_sel_hi:[0,1,1]
	v_pk_fma_f32 v[118:119], v[192:193], v[196:197], v[118:119] op_sel_hi:[0,1,1]
	v_pk_fma_f32 v[180:181], v[192:193], v[186:187], v[116:117] op_sel_hi:[0,1,1]
	v_pk_fma_f32 v[182:183], v[192:193], v[198:199], v[114:115] op_sel_hi:[0,1,1]
	v_mul_f32_e32 v165, v127, v127
	v_mul_f32_e32 v171, v129, v129
	v_mul_f32_e32 v177, v123, v123
	v_mul_f32_e32 v184, v125, v125
	v_cvt_pk_bf16_f32 v114, v126, v127
	v_cvt_pk_bf16_f32 v115, v128, v129
	v_cvt_pk_bf16_f32 v116, v122, v123
	v_cvt_pk_bf16_f32 v117, v124, v125
	v_mul_f32_e32 v123, v119, v119
	v_mul_f32_e32 v125, v121, v121
	v_mul_f32_e32 v127, v183, v183
	v_mul_f32_e32 v129, v181, v181
	v_fmac_f32_e32 v165, v126, v126
	v_fmac_f32_e32 v171, v128, v128
	v_fmac_f32_e32 v177, v122, v122
	v_fmac_f32_e32 v184, v124, v124
	global_store_dwordx4 v[188:189], v[114:117], off sc1
	s_nop 1
	v_fmac_f32_e32 v123, v118, v118
	v_fmac_f32_e32 v125, v120, v120
	v_fmac_f32_e32 v127, v182, v182
	v_add_f32_e32 v114, v165, v171
	v_add_f32_e32 v115, v177, v184
	v_fmac_f32_e32 v129, v180, v180
	v_add_f32_e32 v116, v123, v125
	v_add_f32_e32 v114, v114, v115
	v_add_f32_e32 v115, v127, v129
	v_add_f32_e32 v115, v116, v115
	v_and_b32_e32 v116, 64, v1
	v_add_f32_e32 v115, v114, v115
	v_xor_b32_e32 v114, 16, v1
	v_add_u32_e32 v117, 64, v116
	v_cmp_lt_i32_e64 s[8:9], v114, v117
	v_lshl_add_u64 v[122:123], v[188:189], 0, s[24:25]
	v_cvt_pk_bf16_f32 v118, v118, v119
	v_cndmask_b32_e64 v114, v1, v114, s[8:9]
	v_lshlrev_b32_e32 v114, 2, v114
	v_mov_b32_e32 v116, v115
	s_nop 1
	v_permlane16_swap_b32_e32 v116, v115
	v_cvt_pk_bf16_f32 v119, v120, v121
	v_cvt_pk_bf16_f32 v120, v182, v183
	v_cvt_pk_bf16_f32 v121, v180, v181
	global_store_dwordx4 v[122:123], v[118:121], off sc1
	s_nop 1
	s_waitcnt lgkmcnt(0)
	v_add_f32_e32 v116, v115, v116
	v_xor_b32_e32 v115, 32, v1
	v_cmp_lt_i32_e64 s[8:9], v115, v117
	s_nop 1
	v_cndmask_b32_e64 v115, v1, v115, s[8:9]
	v_lshlrev_b32_e32 v115, 2, v115
	v_mov_b32_e32 v117, v116
	s_nop 1
	v_permlane32_swap_b32_e32 v117, v116
	s_and_saveexec_b64 s[8:9], vcc
	v_readlane_b32 s56, v255, 9
	v_readlane_b32 s57, v255, 10
	v_readlane_b32 s58, v255, 8
	s_cbranch_execz .LBB0_726
	v_lshl_add_u64 v[118:119], v[158:159], 2, s[10:11]
	s_waitcnt lgkmcnt(0)
	v_add_f32_e32 v116, v116, v117
	global_atomic_add_f32 v[118:119], v116, off
; __device__ __forceinline__ float dot4(f32x4 a) { return (a[0] * a[0] + a[1] * a[1]) + (a[2] * a[2] + a[3] * a[3]); }
; __device__ __forceinline__ void store16_wt(void* p, u32x4 v) { asm volatile("global_store_dwordx4 %0, %1, off sc1\n\ts_nop 1" :: "v"(p), "v"(v) : "memory"); }
; __device__ __forceinline__ u32x4 pack8(f32x4 a, f32x4 b) { u32x4 w; w.x = cvt_pk_bf16(a[0], a[1]); w.y = cvt_pk_bf16(a[2], a[3]); w.z = cvt_pk_bf16(b[0], b[1]); w.w = cvt_pk_bf16(b[2], b[3]); return w; }
;     __device__ __forceinline__ void operator()(const f32x4 (&acc)[2][2][4][2], const Unit& u, int wr, int wc, int fr, int fq) const {
;     ...
;         for (int ai = 0; ai < 2; ++ai) {
;             u32x4 xw[4][2]; float rms[4];
; #pragma unroll
;             for (int m = 0; m < 4; ++m) { const int row = row0 + ai * HALF + m * 16; rms[m] = rms1[row];
; #pragma unroll
;                 for (int bj = 0; bj < 2; ++bj) xw[m][bj] = *(const u32x4*)(XB + (size_t)row * 1024 + col0 + bj * HALF); }
; #pragma unroll
;             for (int m = 0; m < 4; ++m) {
;                 const int row = row0 + ai * HALF + m * 16;
;                 float ss = 0.f; const float r = rms[m];
; #pragma unroll
;                 for (int bj = 0; bj < 2; ++bj) { const int col = col0 + bj * HALF; const u32x4 w = xw[m][bj];
;                     const f32x4 a = (f32x4){__builtin_bit_cast(float, w.x << 16), __builtin_bit_cast(float, w.x & 0xffff0000u), __builtin_bit_cast(float, w.y << 16), __builtin_bit_cast(float, w.y & 0xffff0000u)} * r + acc[ai][bj][m][0],
;                                 b = (f32x4){__builtin_bit_cast(float, w.z << 16), __builtin_bit_cast(float, w.z & 0xffff0000u), __builtin_bit_cast(float, w.w << 16), __builtin_bit_cast(float, w.w & 0xffff0000u)} * r + acc[ai][bj][m][1];
;                     ss += dot4(a) + dot4(b);
;                     store16_wt(X1B + (size_t)row * 1024 + col, pack8(a, b)); }
;                 ss += __shfl_xor(ss, 16); ss += __shfl_xor(ss, 32);
;                 if (fq == 0) __hip_atomic_fetch_add(RSS + row, ss, __ATOMIC_RELAXED, __HIP_MEMORY_SCOPE_AGENT);
;             }
.LBB0_726:
	s_or_b64 exec, exec, s[8:9]
	v_lshlrev_b32_e32 v116, 16, v150
	s_waitcnt lgkmcnt(0)
	v_and_b32_e32 v117, 0xffff0000, v150
	v_lshlrev_b32_e32 v118, 16, v151
	v_and_b32_e32 v119, 0xffff0000, v151
	v_pk_fma_f32 v[112:113], v[176:177], v[118:119], v[112:113] op_sel_hi:[0,1,1]
	v_pk_fma_f32 v[110:111], v[176:177], v[116:117], v[110:111] op_sel_hi:[0,1,1]
	v_lshlrev_b32_e32 v116, 16, v152
	v_and_b32_e32 v117, 0xffff0000, v152
	v_lshlrev_b32_e32 v118, 16, v153
	v_and_b32_e32 v119, 0xffff0000, v153
	v_pk_fma_f32 v[118:119], v[176:177], v[118:119], v[108:109] op_sel_hi:[0,1,1]
	v_pk_fma_f32 v[108:109], v[176:177], v[116:117], v[106:107] op_sel_hi:[0,1,1]
	v_mul_f32_e32 v106, v111, v111
	v_mul_f32_e32 v107, v113, v113
	v_fmac_f32_e32 v106, v110, v110
	v_fmac_f32_e32 v107, v112, v112
	v_add_f32_e32 v106, v106, v107
	v_mul_f32_e32 v107, v109, v109
	v_mul_f32_e32 v116, v119, v119
	v_fmac_f32_e32 v107, v108, v108
	v_fmac_f32_e32 v116, v118, v118
	v_add_f32_e32 v107, v107, v116
	v_add_f32_e32 v120, v106, v107
	v_lshl_add_u64 v[106:107], s[12:13], 0, v[178:179]
	v_lshl_add_u64 v[116:117], v[154:155], 1, v[106:107]
	v_cvt_pk_bf16_f32 v106, v110, v111
	v_cvt_pk_bf16_f32 v107, v112, v113
	v_cvt_pk_bf16_f32 v108, v108, v109
	v_cvt_pk_bf16_f32 v109, v118, v119
	global_store_dwordx4 v[116:117], v[106:109], off sc1
	s_nop 1
	v_lshlrev_b32_e32 v106, 16, v146
	v_and_b32_e32 v107, 0xffff0000, v146
	v_lshlrev_b32_e32 v108, 16, v147
	v_and_b32_e32 v109, 0xffff0000, v147
	v_pk_fma_f32 v[104:105], v[176:177], v[108:109], v[104:105] op_sel_hi:[0,1,1]
	v_pk_fma_f32 v[102:103], v[176:177], v[106:107], v[102:103] op_sel_hi:[0,1,1]
	v_lshlrev_b32_e32 v108, 16, v149
	v_and_b32_e32 v109, 0xffff0000, v149
	v_lshlrev_b32_e32 v106, 16, v148
	v_and_b32_e32 v107, 0xffff0000, v148
	v_pk_fma_f32 v[108:109], v[176:177], v[108:109], v[100:101] op_sel_hi:[0,1,1]
	v_mul_f32_e32 v100, v103, v103
	v_mul_f32_e32 v101, v105, v105
	v_pk_fma_f32 v[98:99], v[176:177], v[106:107], v[98:99] op_sel_hi:[0,1,1]
	v_fmac_f32_e32 v100, v102, v102
	v_fmac_f32_e32 v101, v104, v104
	v_add_f32_e32 v100, v100, v101
	v_mul_f32_e32 v101, v99, v99
	v_mul_f32_e32 v106, v109, v109
	v_fmac_f32_e32 v101, v98, v98
	v_fmac_f32_e32 v106, v108, v108
	v_add_f32_e32 v101, v101, v106
	v_add_f32_e32 v100, v100, v101
	v_add_f32_e32 v110, v120, v100
	v_mov_b32_e32 v111, v110
	s_nop 1
	v_permlane16_swap_b32_e32 v111, v110
	v_cvt_pk_bf16_f32 v100, v102, v103
	v_cvt_pk_bf16_f32 v102, v98, v99
	v_lshl_add_u64 v[106:107], v[116:117], 0, s[24:25]
	v_cvt_pk_bf16_f32 v101, v104, v105
	s_waitcnt lgkmcnt(0)
	v_add_f32_e32 v98, v110, v111
	v_mov_b32_e32 v99, v98
	s_nop 1
	v_permlane32_swap_b32_e32 v99, v98
	v_cvt_pk_bf16_f32 v103, v108, v109
	global_store_dwordx4 v[106:107], v[100:103], off sc1
	s_nop 1
	s_and_saveexec_b64 s[8:9], vcc
	s_cbranch_execz .LBB0_728
	v_lshl_add_u64 v[100:101], v[174:175], 2, s[10:11]
	s_waitcnt lgkmcnt(0)
	v_add_f32_e32 v98, v98, v99
	global_atomic_add_f32 v[100:101], v98, off
.LBB0_728:
	s_or_b64 exec, exec, s[8:9]
	v_lshlrev_b32_e32 v98, 16, v142
	s_waitcnt lgkmcnt(0)
	v_and_b32_e32 v99, 0xffff0000, v142
	v_lshlrev_b32_e32 v100, 16, v143
	v_and_b32_e32 v101, 0xffff0000, v143
	v_pk_fma_f32 v[96:97], v[170:171], v[100:101], v[96:97] op_sel_hi:[0,1,1]
	v_pk_fma_f32 v[94:95], v[170:171], v[98:99], v[94:95] op_sel_hi:[0,1,1]
	v_lshlrev_b32_e32 v98, 16, v144
	v_and_b32_e32 v99, 0xffff0000, v144
	v_lshlrev_b32_e32 v100, 16, v145
	v_and_b32_e32 v101, 0xffff0000, v145
	v_pk_fma_f32 v[100:101], v[170:171], v[100:101], v[92:93] op_sel_hi:[0,1,1]
	v_pk_fma_f32 v[92:93], v[170:171], v[98:99], v[90:91] op_sel_hi:[0,1,1]
	v_mul_f32_e32 v90, v95, v95
	v_mul_f32_e32 v91, v97, v97
	v_fmac_f32_e32 v90, v94, v94
	v_fmac_f32_e32 v91, v96, v96
	v_add_f32_e32 v90, v90, v91
	v_mul_f32_e32 v91, v93, v93
	v_mul_f32_e32 v98, v101, v101
	v_fmac_f32_e32 v91, v92, v92
	v_fmac_f32_e32 v98, v100, v100
	v_add_f32_e32 v91, v91, v98
	v_add_f32_e32 v102, v90, v91
	v_lshl_add_u64 v[90:91], s[12:13], 0, v[172:173]
	v_lshl_add_u64 v[98:99], v[154:155], 1, v[90:91]
	v_cvt_pk_bf16_f32 v90, v94, v95
	v_cvt_pk_bf16_f32 v91, v96, v97
	v_cvt_pk_bf16_f32 v92, v92, v93
	v_cvt_pk_bf16_f32 v93, v100, v101
	global_store_dwordx4 v[98:99], v[90:93], off sc1
	s_nop 1
	v_lshlrev_b32_e32 v90, 16, v138
	v_and_b32_e32 v91, 0xffff0000, v138
	v_lshlrev_b32_e32 v92, 16, v139
	v_and_b32_e32 v93, 0xffff0000, v139
	v_pk_fma_f32 v[88:89], v[170:171], v[92:93], v[88:89] op_sel_hi:[0,1,1]
	v_pk_fma_f32 v[86:87], v[170:171], v[90:91], v[86:87] op_sel_hi:[0,1,1]
	v_lshlrev_b32_e32 v92, 16, v141
	v_and_b32_e32 v93, 0xffff0000, v141
	v_lshlrev_b32_e32 v90, 16, v140
	v_and_b32_e32 v91, 0xffff0000, v140
	v_pk_fma_f32 v[92:93], v[170:171], v[92:93], v[84:85] op_sel_hi:[0,1,1]
	v_mul_f32_e32 v84, v87, v87
	v_mul_f32_e32 v85, v89, v89
	v_pk_fma_f32 v[82:83], v[170:171], v[90:91], v[82:83] op_sel_hi:[0,1,1]
	v_fmac_f32_e32 v84, v86, v86
	v_fmac_f32_e32 v85, v88, v88
	v_add_f32_e32 v84, v84, v85
	v_mul_f32_e32 v85, v83, v83
	v_mul_f32_e32 v90, v93, v93
	v_fmac_f32_e32 v85, v82, v82
	v_fmac_f32_e32 v90, v92, v92
	v_add_f32_e32 v85, v85, v90
	v_add_f32_e32 v84, v84, v85
	v_add_f32_e32 v94, v102, v84
	v_mov_b32_e32 v95, v94
	s_nop 1
	v_permlane16_swap_b32_e32 v95, v94
	v_cvt_pk_bf16_f32 v84, v86, v87
	v_cvt_pk_bf16_f32 v86, v82, v83
	s_mov_b64 s[8:9], 0x100
	v_lshl_add_u64 v[90:91], v[98:99], 0, s[8:9]
	s_waitcnt lgkmcnt(0)
	v_add_f32_e32 v82, v94, v95
	v_mov_b32_e32 v83, v82
	s_nop 1
	v_permlane32_swap_b32_e32 v83, v82
	v_cvt_pk_bf16_f32 v85, v88, v89
	v_cvt_pk_bf16_f32 v87, v92, v93
	global_store_dwordx4 v[90:91], v[84:87], off sc1
	s_nop 1
	s_and_saveexec_b64 s[24:25], vcc
	s_cbranch_execz .LBB0_730
	v_lshl_add_u64 v[84:85], v[168:169], 2, s[10:11]
	s_waitcnt lgkmcnt(0)
	v_add_f32_e32 v82, v82, v83
	global_atomic_add_f32 v[84:85], v82, off
; __device__ __forceinline__ float dot4(f32x4 a) { return (a[0] * a[0] + a[1] * a[1]) + (a[2] * a[2] + a[3] * a[3]); }
; __device__ __forceinline__ void store16_wt(void* p, u32x4 v) { asm volatile("global_store_dwordx4 %0, %1, off sc1\n\ts_nop 1" :: "v"(p), "v"(v) : "memory"); }
; __device__ __forceinline__ u32x4 pack8(f32x4 a, f32x4 b) { u32x4 w; w.x = cvt_pk_bf16(a[0], a[1]); w.y = cvt_pk_bf16(a[2], a[3]); w.z = cvt_pk_bf16(b[0], b[1]); w.w = cvt_pk_bf16(b[2], b[3]); return w; }
;     __device__ __forceinline__ void operator()(const f32x4 (&acc)[2][2][4][2], const Unit& u, int wr, int wc, int fr, int fq) const {
;     ...
;         for (int ai = 0; ai < 2; ++ai) {
;             u32x4 xw[4][2]; float rms[4];
; #pragma unroll
;             for (int m = 0; m < 4; ++m) { const int row = row0 + ai * HALF + m * 16; rms[m] = rms1[row];
; #pragma unroll
;                 for (int bj = 0; bj < 2; ++bj) xw[m][bj] = *(const u32x4*)(XB + (size_t)row * 1024 + col0 + bj * HALF); }
; #pragma unroll
;             for (int m = 0; m < 4; ++m) {
;                 const int row = row0 + ai * HALF + m * 16;
;                 float ss = 0.f; const float r = rms[m];
; #pragma unroll
;                 for (int bj = 0; bj < 2; ++bj) { const int col = col0 + bj * HALF; const u32x4 w = xw[m][bj];
;                     const f32x4 a = (f32x4){__builtin_bit_cast(float, w.x << 16), __builtin_bit_cast(float, w.x & 0xffff0000u), __builtin_bit_cast(float, w.y << 16), __builtin_bit_cast(float, w.y & 0xffff0000u)} * r + acc[ai][bj][m][0],
;                                 b = (f32x4){__builtin_bit_cast(float, w.z << 16), __builtin_bit_cast(float, w.z & 0xffff0000u), __builtin_bit_cast(float, w.w << 16), __builtin_bit_cast(float, w.w & 0xffff0000u)} * r + acc[ai][bj][m][1];
;                     ss += dot4(a) + dot4(b);
;                     store16_wt(X1B + (size_t)row * 1024 + col, pack8(a, b)); }
;                 ss += __shfl_xor(ss, 16); ss += __shfl_xor(ss, 32);
;                 if (fq == 0) __hip_atomic_fetch_add(RSS + row, ss, __ATOMIC_RELAXED, __HIP_MEMORY_SCOPE_AGENT);
;             }
.LBB0_730:
	s_or_b64 exec, exec, s[24:25]
	v_lshlrev_b32_e32 v82, 16, v134
	s_waitcnt lgkmcnt(0)
	v_and_b32_e32 v83, 0xffff0000, v134
	v_lshlrev_b32_e32 v84, 16, v135
	v_and_b32_e32 v85, 0xffff0000, v135
	v_pk_fma_f32 v[80:81], v[164:165], v[84:85], v[80:81] op_sel_hi:[0,1,1]
	v_pk_fma_f32 v[78:79], v[164:165], v[82:83], v[78:79] op_sel_hi:[0,1,1]
	v_lshlrev_b32_e32 v82, 16, v136
	v_and_b32_e32 v83, 0xffff0000, v136
	v_lshlrev_b32_e32 v84, 16, v137
	v_and_b32_e32 v85, 0xffff0000, v137
	v_pk_fma_f32 v[84:85], v[164:165], v[84:85], v[76:77] op_sel_hi:[0,1,1]
	v_pk_fma_f32 v[76:77], v[164:165], v[82:83], v[74:75] op_sel_hi:[0,1,1]
	v_mul_f32_e32 v74, v79, v79
	v_mul_f32_e32 v75, v81, v81
	v_fmac_f32_e32 v74, v78, v78
	v_fmac_f32_e32 v75, v80, v80
	v_add_f32_e32 v74, v74, v75
	v_mul_f32_e32 v75, v77, v77
	v_mul_f32_e32 v82, v85, v85
	v_fmac_f32_e32 v75, v76, v76
	v_fmac_f32_e32 v82, v84, v84
	v_add_f32_e32 v75, v75, v82
	v_add_f32_e32 v86, v74, v75
	v_lshl_add_u64 v[74:75], s[12:13], 0, v[166:167]
	v_lshl_add_u64 v[82:83], v[154:155], 1, v[74:75]
	v_cvt_pk_bf16_f32 v74, v78, v79
	v_cvt_pk_bf16_f32 v75, v80, v81
	v_cvt_pk_bf16_f32 v76, v76, v77
	v_cvt_pk_bf16_f32 v77, v84, v85
	global_store_dwordx4 v[82:83], v[74:77], off sc1
	s_nop 1
	v_lshlrev_b32_e32 v74, 16, v130
	v_and_b32_e32 v75, 0xffff0000, v130
	v_lshlrev_b32_e32 v76, 16, v131
	v_and_b32_e32 v77, 0xffff0000, v131
	v_pk_fma_f32 v[72:73], v[164:165], v[76:77], v[72:73] op_sel_hi:[0,1,1]
	v_pk_fma_f32 v[70:71], v[164:165], v[74:75], v[70:71] op_sel_hi:[0,1,1]
	v_lshlrev_b32_e32 v76, 16, v133
	v_and_b32_e32 v77, 0xffff0000, v133
	v_lshlrev_b32_e32 v74, 16, v132
	v_and_b32_e32 v75, 0xffff0000, v132
	v_pk_fma_f32 v[76:77], v[164:165], v[76:77], v[68:69] op_sel_hi:[0,1,1]
	v_mul_f32_e32 v68, v71, v71
	v_mul_f32_e32 v69, v73, v73
	v_pk_fma_f32 v[66:67], v[164:165], v[74:75], v[66:67] op_sel_hi:[0,1,1]
	v_fmac_f32_e32 v68, v70, v70
	v_fmac_f32_e32 v69, v72, v72
	v_add_f32_e32 v68, v68, v69
	v_mul_f32_e32 v69, v67, v67
	v_mul_f32_e32 v74, v77, v77
	v_fmac_f32_e32 v69, v66, v66
	v_fmac_f32_e32 v74, v76, v76
	v_add_f32_e32 v69, v69, v74
	v_add_f32_e32 v68, v68, v69
	v_add_f32_e32 v78, v86, v68
	v_mov_b32_e32 v79, v78
	s_nop 1
	v_permlane16_swap_b32_e32 v79, v78
	v_cvt_pk_bf16_f32 v68, v70, v71
	v_cvt_pk_bf16_f32 v70, v66, v67
	v_lshl_add_u64 v[74:75], v[82:83], 0, s[8:9]
	v_cvt_pk_bf16_f32 v69, v72, v73
	s_waitcnt lgkmcnt(0)
	v_add_f32_e32 v66, v78, v79
	v_mov_b32_e32 v67, v66
	s_nop 1
	v_permlane32_swap_b32_e32 v67, v66
	v_cvt_pk_bf16_f32 v71, v76, v77
	global_store_dwordx4 v[74:75], v[68:71], off sc1
	s_nop 1
	s_and_saveexec_b64 s[8:9], vcc
	s_cbranch_execz .LBB0_732
	v_lshl_add_u64 v[68:69], v[162:163], 2, s[10:11]
	s_waitcnt lgkmcnt(0)
	v_add_f32_e32 v66, v66, v67
	global_atomic_add_f32 v[68:69], v66, off
.LBB0_732:
	s_or_b64 exec, exec, s[8:9]
	v_add_u32_e32 v108, 0x80, v158
	v_ashrrev_i32_e32 v109, 31, v108
	v_lshlrev_b64 v[120:121], 11, v[108:109]
	s_waitcnt lgkmcnt(0)
	v_add_u32_e32 v102, 0x90, v158
	v_add_u32_e32 v96, 0xa0, v158
	v_add_u32_e32 v90, 0xb0, v158
	v_ashrrev_i32_e32 v103, 31, v102
	v_ashrrev_i32_e32 v97, 31, v96
	v_ashrrev_i32_e32 v91, 31, v90
	v_lshlrev_b64 v[106:107], 11, v[102:103]
	v_lshlrev_b64 v[100:101], 11, v[96:97]
	v_lshlrev_b64 v[94:95], 11, v[90:91]
	v_lshl_add_u64 v[124:125], v[156:157], 0, v[94:95]
	s_nop 0
	v_lshl_add_u64 v[120:121], s[12:13], 0, v[120:121]
	v_lshl_add_u64 v[120:121], v[154:155], 1, v[120:121]
	s_mov_b64 s[8:9], 0x100
	v_lshlrev_b32_e32 v124, 16, v200
	v_and_b32_e32 v125, 0xffff0000, v200
	v_lshlrev_b32_e32 v200, 16, v201
	v_and_b32_e32 v201, 0xffff0000, v201
	v_lshlrev_b32_e32 v126, 16, v202
	v_and_b32_e32 v127, 0xffff0000, v202
	v_lshlrev_b32_e32 v202, 16, v203
	v_and_b32_e32 v203, 0xffff0000, v203
	v_lshlrev_b32_e32 v128, 16, v204
	v_and_b32_e32 v129, 0xffff0000, v204
	v_lshlrev_b32_e32 v204, 16, v205
	v_and_b32_e32 v205, 0xffff0000, v205
	v_lshlrev_b32_e32 v130, 16, v206
	v_and_b32_e32 v131, 0xffff0000, v206
	v_lshlrev_b32_e32 v206, 16, v207
	v_and_b32_e32 v207, 0xffff0000, v207
	v_pk_fma_f32 v[64:65], v[236:237], v[200:201], v[64:65] op_sel_hi:[0,1,1]
	v_pk_fma_f32 v[62:63], v[236:237], v[124:125], v[62:63] op_sel_hi:[0,1,1]
	v_pk_fma_f32 v[60:61], v[236:237], v[202:203], v[60:61] op_sel_hi:[0,1,1]
	v_pk_fma_f32 v[58:59], v[236:237], v[126:127], v[58:59] op_sel_hi:[0,1,1]
	v_pk_fma_f32 v[56:57], v[236:237], v[204:205], v[56:57] op_sel_hi:[0,1,1]
	v_pk_fma_f32 v[54:55], v[236:237], v[128:129], v[54:55] op_sel_hi:[0,1,1]
	v_pk_fma_f32 v[200:201], v[236:237], v[206:207], v[52:53] op_sel_hi:[0,1,1]
	v_pk_fma_f32 v[202:203], v[236:237], v[130:131], v[50:51] op_sel_hi:[0,1,1]
	v_mul_f32_e32 v245, v63, v63
	v_mul_f32_e32 v241, v65, v65
	v_mul_f32_e32 v239, v59, v59
	v_mul_f32_e32 v204, v61, v61
	v_cvt_pk_bf16_f32 v50, v62, v63
	v_cvt_pk_bf16_f32 v51, v64, v65
	v_cvt_pk_bf16_f32 v52, v58, v59
	v_cvt_pk_bf16_f32 v53, v60, v61
	v_mul_f32_e32 v59, v55, v55
	v_mul_f32_e32 v61, v57, v57
	v_mul_f32_e32 v63, v203, v203
	v_mul_f32_e32 v65, v201, v201
	v_fmac_f32_e32 v245, v62, v62
	v_fmac_f32_e32 v241, v64, v64
	v_fmac_f32_e32 v239, v58, v58
	v_fmac_f32_e32 v204, v60, v60
	v_fmac_f32_e32 v59, v54, v54
	v_fmac_f32_e32 v61, v56, v56
	v_fmac_f32_e32 v63, v202, v202
	v_fmac_f32_e32 v65, v200, v200
	global_store_dwordx4 v[120:121], v[50:53], off sc1
	s_nop 1
	v_add_f32_e32 v50, v245, v241
	v_add_f32_e32 v51, v239, v204
	v_add_f32_e32 v52, v59, v61
	v_add_f32_e32 v53, v63, v65
	v_add_f32_e32 v50, v50, v51
	v_add_f32_e32 v51, v52, v53
	v_add_f32_e32 v50, v50, v51
	v_mov_b32_e32 v51, v50
	s_nop 1
	v_permlane16_swap_b32_e32 v51, v50
	v_lshl_add_u64 v[58:59], v[120:121], 0, s[8:9]
	v_cvt_pk_bf16_f32 v52, v54, v55
	v_cvt_pk_bf16_f32 v53, v56, v57
	v_cvt_pk_bf16_f32 v54, v202, v203
	s_waitcnt lgkmcnt(0)
	v_add_f32_e32 v50, v50, v51
	v_mov_b32_e32 v51, v50
	s_nop 1
	v_permlane32_swap_b32_e32 v51, v50
	v_cvt_pk_bf16_f32 v55, v200, v201
	global_store_dwordx4 v[58:59], v[52:55], off sc1
	s_nop 1
	s_and_saveexec_b64 s[24:25], vcc
	s_cbranch_execz .LBB0_734
	v_lshl_add_u64 v[52:53], v[108:109], 2, s[10:11]
	s_waitcnt lgkmcnt(0)
	v_add_f32_e32 v50, v50, v51
	global_atomic_add_f32 v[52:53], v50, off
; __device__ __forceinline__ float dot4(f32x4 a) { return (a[0] * a[0] + a[1] * a[1]) + (a[2] * a[2] + a[3] * a[3]); }
; __device__ __forceinline__ void store16_wt(void* p, u32x4 v) { asm volatile("global_store_dwordx4 %0, %1, off sc1\n\ts_nop 1" :: "v"(p), "v"(v) : "memory"); }
; __device__ __forceinline__ u32x4 pack8(f32x4 a, f32x4 b) { u32x4 w; w.x = cvt_pk_bf16(a[0], a[1]); w.y = cvt_pk_bf16(a[2], a[3]); w.z = cvt_pk_bf16(b[0], b[1]); w.w = cvt_pk_bf16(b[2], b[3]); return w; }
;     __device__ __forceinline__ void operator()(const f32x4 (&acc)[2][2][4][2], const Unit& u, int wr, int wc, int fr, int fq) const {
;     ...
;         for (int ai = 0; ai < 2; ++ai) {
;             u32x4 xw[4][2]; float rms[4];
; #pragma unroll
;             for (int m = 0; m < 4; ++m) { const int row = row0 + ai * HALF + m * 16; rms[m] = rms1[row];
; #pragma unroll
;                 for (int bj = 0; bj < 2; ++bj) xw[m][bj] = *(const u32x4*)(XB + (size_t)row * 1024 + col0 + bj * HALF); }
; #pragma unroll
;             for (int m = 0; m < 4; ++m) {
;                 const int row = row0 + ai * HALF + m * 16;
;                 float ss = 0.f; const float r = rms[m];
; #pragma unroll
;                 for (int bj = 0; bj < 2; ++bj) { const int col = col0 + bj * HALF; const u32x4 w = xw[m][bj];
;                     const f32x4 a = (f32x4){__builtin_bit_cast(float, w.x << 16), __builtin_bit_cast(float, w.x & 0xffff0000u), __builtin_bit_cast(float, w.y << 16), __builtin_bit_cast(float, w.y & 0xffff0000u)} * r + acc[ai][bj][m][0],
;                                 b = (f32x4){__builtin_bit_cast(float, w.z << 16), __builtin_bit_cast(float, w.z & 0xffff0000u), __builtin_bit_cast(float, w.w << 16), __builtin_bit_cast(float, w.w & 0xffff0000u)} * r + acc[ai][bj][m][1];
;                     ss += dot4(a) + dot4(b);
;                     store16_wt(X1B + (size_t)row * 1024 + col, pack8(a, b)); }
;                 ss += __shfl_xor(ss, 16); ss += __shfl_xor(ss, 32);
;                 if (fq == 0) __hip_atomic_fetch_add(RSS + row, ss, __ATOMIC_RELAXED, __HIP_MEMORY_SCOPE_AGENT);
;             }
.LBB0_734:
	s_or_b64 exec, exec, s[24:25]
	v_lshlrev_b32_e32 v50, 16, v208
	s_waitcnt lgkmcnt(0)
	v_and_b32_e32 v51, 0xffff0000, v208
	v_lshlrev_b32_e32 v52, 16, v209
	v_and_b32_e32 v53, 0xffff0000, v209
	v_pk_fma_f32 v[48:49], v[238:239], v[52:53], v[48:49] op_sel_hi:[0,1,1]
	v_pk_fma_f32 v[46:47], v[238:239], v[50:51], v[46:47] op_sel_hi:[0,1,1]
	v_lshlrev_b32_e32 v50, 16, v210
	v_and_b32_e32 v51, 0xffff0000, v210
	v_lshlrev_b32_e32 v52, 16, v211
	v_and_b32_e32 v53, 0xffff0000, v211
	v_pk_fma_f32 v[52:53], v[238:239], v[52:53], v[44:45] op_sel_hi:[0,1,1]
	v_pk_fma_f32 v[44:45], v[238:239], v[50:51], v[42:43] op_sel_hi:[0,1,1]
	v_mul_f32_e32 v42, v47, v47
	v_mul_f32_e32 v43, v49, v49
	v_fmac_f32_e32 v42, v46, v46
	v_fmac_f32_e32 v43, v48, v48
	v_add_f32_e32 v42, v42, v43
	v_mul_f32_e32 v43, v45, v45
	v_mul_f32_e32 v50, v53, v53
	v_fmac_f32_e32 v43, v44, v44
	v_fmac_f32_e32 v50, v52, v52
	v_add_f32_e32 v43, v43, v50
	v_add_f32_e32 v54, v42, v43
	v_lshl_add_u64 v[42:43], s[12:13], 0, v[106:107]
	v_lshl_add_u64 v[50:51], v[154:155], 1, v[42:43]
	v_cvt_pk_bf16_f32 v42, v46, v47
	v_cvt_pk_bf16_f32 v43, v48, v49
	v_cvt_pk_bf16_f32 v44, v44, v45
	v_cvt_pk_bf16_f32 v45, v52, v53
	global_store_dwordx4 v[50:51], v[42:45], off sc1
	s_nop 1
	v_lshlrev_b32_e32 v42, 16, v212
	v_and_b32_e32 v43, 0xffff0000, v212
	v_lshlrev_b32_e32 v44, 16, v213
	v_and_b32_e32 v45, 0xffff0000, v213
	v_pk_fma_f32 v[40:41], v[238:239], v[44:45], v[40:41] op_sel_hi:[0,1,1]
	v_pk_fma_f32 v[38:39], v[238:239], v[42:43], v[38:39] op_sel_hi:[0,1,1]
	v_lshlrev_b32_e32 v44, 16, v215
	v_and_b32_e32 v45, 0xffff0000, v215
	v_lshlrev_b32_e32 v42, 16, v214
	v_and_b32_e32 v43, 0xffff0000, v214
	v_pk_fma_f32 v[44:45], v[238:239], v[44:45], v[36:37] op_sel_hi:[0,1,1]
	v_mul_f32_e32 v36, v39, v39
	v_mul_f32_e32 v37, v41, v41
	v_pk_fma_f32 v[34:35], v[238:239], v[42:43], v[34:35] op_sel_hi:[0,1,1]
	v_fmac_f32_e32 v36, v38, v38
	v_fmac_f32_e32 v37, v40, v40
	v_add_f32_e32 v36, v36, v37
	v_mul_f32_e32 v37, v35, v35
	v_mul_f32_e32 v42, v45, v45
	v_fmac_f32_e32 v37, v34, v34
	v_fmac_f32_e32 v42, v44, v44
	v_add_f32_e32 v37, v37, v42
	v_add_f32_e32 v36, v36, v37
	v_add_f32_e32 v46, v54, v36
	v_mov_b32_e32 v47, v46
	s_nop 1
	v_permlane16_swap_b32_e32 v47, v46
	v_cvt_pk_bf16_f32 v36, v38, v39
	v_cvt_pk_bf16_f32 v38, v34, v35
	v_lshl_add_u64 v[42:43], v[50:51], 0, s[8:9]
	v_cvt_pk_bf16_f32 v37, v40, v41
	s_waitcnt lgkmcnt(0)
	v_add_f32_e32 v34, v46, v47
	v_mov_b32_e32 v35, v34
	s_nop 1
	v_permlane32_swap_b32_e32 v35, v34
	v_cvt_pk_bf16_f32 v39, v44, v45
	global_store_dwordx4 v[42:43], v[36:39], off sc1
	s_nop 1
	s_and_saveexec_b64 s[8:9], vcc
	s_cbranch_execz .LBB0_736
	v_lshl_add_u64 v[36:37], v[102:103], 2, s[10:11]
	s_waitcnt lgkmcnt(0)
	v_add_f32_e32 v34, v34, v35
	global_atomic_add_f32 v[36:37], v34, off
; __device__ __forceinline__ float dot4(f32x4 a) { return (a[0] * a[0] + a[1] * a[1]) + (a[2] * a[2] + a[3] * a[3]); }
; __device__ __forceinline__ void store16_wt(void* p, u32x4 v) { asm volatile("global_store_dwordx4 %0, %1, off sc1\n\ts_nop 1" :: "v"(p), "v"(v) : "memory"); }
; __device__ __forceinline__ u32x4 pack8(f32x4 a, f32x4 b) { u32x4 w; w.x = cvt_pk_bf16(a[0], a[1]); w.y = cvt_pk_bf16(a[2], a[3]); w.z = cvt_pk_bf16(b[0], b[1]); w.w = cvt_pk_bf16(b[2], b[3]); return w; }
;     __device__ __forceinline__ void operator()(const f32x4 (&acc)[2][2][4][2], const Unit& u, int wr, int wc, int fr, int fq) const {
;     ...
;         for (int ai = 0; ai < 2; ++ai) {
;             u32x4 xw[4][2]; float rms[4];
; #pragma unroll
;             for (int m = 0; m < 4; ++m) { const int row = row0 + ai * HALF + m * 16; rms[m] = rms1[row];
; #pragma unroll
;                 for (int bj = 0; bj < 2; ++bj) xw[m][bj] = *(const u32x4*)(XB + (size_t)row * 1024 + col0 + bj * HALF); }
; #pragma unroll
;             for (int m = 0; m < 4; ++m) {
;                 const int row = row0 + ai * HALF + m * 16;
;                 float ss = 0.f; const float r = rms[m];
; #pragma unroll
;                 for (int bj = 0; bj < 2; ++bj) { const int col = col0 + bj * HALF; const u32x4 w = xw[m][bj];
;                     const f32x4 a = (f32x4){__builtin_bit_cast(float, w.x << 16), __builtin_bit_cast(float, w.x & 0xffff0000u), __builtin_bit_cast(float, w.y << 16), __builtin_bit_cast(float, w.y & 0xffff0000u)} * r + acc[ai][bj][m][0],
;                                 b = (f32x4){__builtin_bit_cast(float, w.z << 16), __builtin_bit_cast(float, w.z & 0xffff0000u), __builtin_bit_cast(float, w.w << 16), __builtin_bit_cast(float, w.w & 0xffff0000u)} * r + acc[ai][bj][m][1];
;                     ss += dot4(a) + dot4(b);
;                     store16_wt(X1B + (size_t)row * 1024 + col, pack8(a, b)); }
;                 ss += __shfl_xor(ss, 16); ss += __shfl_xor(ss, 32);
;                 if (fq == 0) __hip_atomic_fetch_add(RSS + row, ss, __ATOMIC_RELAXED, __HIP_MEMORY_SCOPE_AGENT);
;             }
.LBB0_736:
	s_or_b64 exec, exec, s[8:9]
	v_lshlrev_b32_e32 v34, 16, v216
	s_waitcnt lgkmcnt(0)
	v_and_b32_e32 v35, 0xffff0000, v216
	v_lshlrev_b32_e32 v36, 16, v217
	v_and_b32_e32 v37, 0xffff0000, v217
	v_pk_fma_f32 v[32:33], v[240:241], v[36:37], v[32:33] op_sel_hi:[0,1,1]
	v_pk_fma_f32 v[30:31], v[240:241], v[34:35], v[30:31] op_sel_hi:[0,1,1]
	v_lshlrev_b32_e32 v34, 16, v218
	v_and_b32_e32 v35, 0xffff0000, v218
	v_lshlrev_b32_e32 v36, 16, v219
	v_and_b32_e32 v37, 0xffff0000, v219
	v_pk_fma_f32 v[36:37], v[240:241], v[36:37], v[28:29] op_sel_hi:[0,1,1]
	v_pk_fma_f32 v[28:29], v[240:241], v[34:35], v[26:27] op_sel_hi:[0,1,1]
	v_mul_f32_e32 v26, v31, v31
	v_mul_f32_e32 v27, v33, v33
	v_fmac_f32_e32 v26, v30, v30
	v_fmac_f32_e32 v27, v32, v32
	v_add_f32_e32 v26, v26, v27
	v_mul_f32_e32 v27, v29, v29
	v_mul_f32_e32 v34, v37, v37
	v_fmac_f32_e32 v27, v28, v28
	v_fmac_f32_e32 v34, v36, v36
	v_add_f32_e32 v27, v27, v34
	v_add_f32_e32 v38, v26, v27
	v_lshl_add_u64 v[26:27], s[12:13], 0, v[100:101]
	v_lshl_add_u64 v[34:35], v[154:155], 1, v[26:27]
	v_cvt_pk_bf16_f32 v26, v30, v31
	v_cvt_pk_bf16_f32 v27, v32, v33
	v_cvt_pk_bf16_f32 v28, v28, v29
	v_cvt_pk_bf16_f32 v29, v36, v37
	global_store_dwordx4 v[34:35], v[26:29], off sc1
	s_nop 1
	v_lshlrev_b32_e32 v26, 16, v220
	v_and_b32_e32 v27, 0xffff0000, v220
	v_lshlrev_b32_e32 v28, 16, v221
	v_and_b32_e32 v29, 0xffff0000, v221
	v_pk_fma_f32 v[24:25], v[240:241], v[28:29], v[24:25] op_sel_hi:[0,1,1]
	v_pk_fma_f32 v[22:23], v[240:241], v[26:27], v[22:23] op_sel_hi:[0,1,1]
	v_lshlrev_b32_e32 v28, 16, v223
	v_and_b32_e32 v29, 0xffff0000, v223
	v_lshlrev_b32_e32 v26, 16, v222
	v_and_b32_e32 v27, 0xffff0000, v222
	v_pk_fma_f32 v[28:29], v[240:241], v[28:29], v[20:21] op_sel_hi:[0,1,1]
	v_mul_f32_e32 v20, v23, v23
	v_mul_f32_e32 v21, v25, v25
	v_pk_fma_f32 v[18:19], v[240:241], v[26:27], v[18:19] op_sel_hi:[0,1,1]
	v_fmac_f32_e32 v20, v22, v22
	v_fmac_f32_e32 v21, v24, v24
	v_add_f32_e32 v20, v20, v21
	v_mul_f32_e32 v21, v19, v19
	v_mul_f32_e32 v26, v29, v29
	v_fmac_f32_e32 v21, v18, v18
	v_fmac_f32_e32 v26, v28, v28
	v_add_f32_e32 v21, v21, v26
	v_add_f32_e32 v20, v20, v21
	v_add_f32_e32 v30, v38, v20
	v_mov_b32_e32 v31, v30
	s_nop 1
	v_permlane16_swap_b32_e32 v31, v30
	v_cvt_pk_bf16_f32 v20, v22, v23
	v_cvt_pk_bf16_f32 v22, v18, v19
	s_mov_b64 s[8:9], 0x100
	v_lshl_add_u64 v[26:27], v[34:35], 0, s[8:9]
	s_waitcnt lgkmcnt(0)
	v_add_f32_e32 v18, v30, v31
	v_mov_b32_e32 v19, v18
	s_nop 1
	v_permlane32_swap_b32_e32 v19, v18
	v_cvt_pk_bf16_f32 v21, v24, v25
	v_cvt_pk_bf16_f32 v23, v28, v29
	global_store_dwordx4 v[26:27], v[20:23], off sc1
	s_nop 1
	s_and_saveexec_b64 s[24:25], vcc
	s_cbranch_execz .LBB0_738
	v_lshl_add_u64 v[20:21], v[96:97], 2, s[10:11]
	s_waitcnt lgkmcnt(0)
	v_add_f32_e32 v18, v18, v19
	global_atomic_add_f32 v[20:21], v18, off
.LBB0_738:
	s_or_b64 exec, exec, s[24:25]
	v_lshlrev_b32_e32 v18, 16, v224
	s_waitcnt lgkmcnt(0)
	v_and_b32_e32 v19, 0xffff0000, v224
	v_lshlrev_b32_e32 v20, 16, v225
	v_and_b32_e32 v21, 0xffff0000, v225
	v_pk_fma_f32 v[16:17], v[244:245], v[20:21], v[16:17] op_sel_hi:[0,1,1]
	v_pk_fma_f32 v[14:15], v[244:245], v[18:19], v[14:15] op_sel_hi:[0,1,1]
	v_lshlrev_b32_e32 v18, 16, v226
	v_and_b32_e32 v19, 0xffff0000, v226
	v_lshlrev_b32_e32 v20, 16, v227
	v_and_b32_e32 v21, 0xffff0000, v227
	v_pk_fma_f32 v[20:21], v[244:245], v[20:21], v[12:13] op_sel_hi:[0,1,1]
	v_pk_fma_f32 v[12:13], v[244:245], v[18:19], v[10:11] op_sel_hi:[0,1,1]
	v_mul_f32_e32 v10, v15, v15
	v_mul_f32_e32 v11, v17, v17
	v_fmac_f32_e32 v10, v14, v14
	v_fmac_f32_e32 v11, v16, v16
	v_add_f32_e32 v10, v10, v11
	v_mul_f32_e32 v11, v13, v13
	v_mul_f32_e32 v18, v21, v21
	v_fmac_f32_e32 v11, v12, v12
	v_fmac_f32_e32 v18, v20, v20
	v_add_f32_e32 v11, v11, v18
	v_add_f32_e32 v22, v10, v11
	v_lshl_add_u64 v[10:11], s[12:13], 0, v[94:95]
	v_lshl_add_u64 v[18:19], v[154:155], 1, v[10:11]
	v_cvt_pk_bf16_f32 v10, v14, v15
	v_cvt_pk_bf16_f32 v11, v16, v17
	v_cvt_pk_bf16_f32 v12, v12, v13
	v_cvt_pk_bf16_f32 v13, v20, v21
	global_store_dwordx4 v[18:19], v[10:13], off sc1
	s_nop 1
	v_lshlrev_b32_e32 v10, 16, v232
	v_and_b32_e32 v11, 0xffff0000, v232
	v_lshlrev_b32_e32 v12, 16, v233
	v_and_b32_e32 v13, 0xffff0000, v233
	v_pk_fma_f32 v[8:9], v[244:245], v[12:13], v[8:9] op_sel_hi:[0,1,1]
	v_pk_fma_f32 v[6:7], v[244:245], v[10:11], v[6:7] op_sel_hi:[0,1,1]
	v_lshlrev_b32_e32 v12, 16, v235
	v_and_b32_e32 v13, 0xffff0000, v235
	v_lshlrev_b32_e32 v10, 16, v234
	v_and_b32_e32 v11, 0xffff0000, v234
	v_pk_fma_f32 v[12:13], v[244:245], v[12:13], v[4:5] op_sel_hi:[0,1,1]
	v_mul_f32_e32 v4, v7, v7
	v_mul_f32_e32 v5, v9, v9
	v_pk_fma_f32 v[2:3], v[244:245], v[10:11], v[2:3] op_sel_hi:[0,1,1]
	v_fmac_f32_e32 v4, v6, v6
	v_fmac_f32_e32 v5, v8, v8
	v_add_f32_e32 v4, v4, v5
	v_mul_f32_e32 v5, v3, v3
	v_mul_f32_e32 v10, v13, v13
	v_fmac_f32_e32 v5, v2, v2
	v_fmac_f32_e32 v10, v12, v12
	v_add_f32_e32 v5, v5, v10
	v_add_f32_e32 v4, v4, v5
	v_add_f32_e32 v14, v22, v4
	v_mov_b32_e32 v15, v14
	s_nop 1
	v_permlane16_swap_b32_e32 v15, v14
	v_cvt_pk_bf16_f32 v4, v6, v7
	v_cvt_pk_bf16_f32 v6, v2, v3
	v_lshl_add_u64 v[10:11], v[18:19], 0, s[8:9]
	v_cvt_pk_bf16_f32 v5, v8, v9
	s_waitcnt lgkmcnt(0)
	v_add_f32_e32 v2, v14, v15
	v_mov_b32_e32 v3, v2
	s_nop 1
	v_permlane32_swap_b32_e32 v3, v2
	v_cvt_pk_bf16_f32 v7, v12, v13
	global_store_dwordx4 v[10:11], v[4:7], off sc1
	s_nop 1
	s_and_saveexec_b64 s[8:9], vcc
	s_cbranch_execz .LBB0_740
	v_lshl_add_u64 v[4:5], v[90:91], 2, s[10:11]
	s_waitcnt lgkmcnt(0)
	v_add_f32_e32 v2, v2, v3
	global_atomic_add_f32 v[4:5], v2, off

; __device__ __forceinline__ float dot4(f32x4 a) { return (a[0] * a[0] + a[1] * a[1]) + (a[2] * a[2] + a[3] * a[3]); }
; __device__ __forceinline__ void store16_wt(void* p, u32x4 v) { asm volatile("global_store_dwordx4 %0, %1, off sc1\n\ts_nop 1" :: "v"(p), "v"(v) : "memory"); }
; __device__ __forceinline__ u32x4 pack8(f32x4 a, f32x4 b) { u32x4 w; w.x = cvt_pk_bf16(a[0], a[1]); w.y = cvt_pk_bf16(a[2], a[3]); w.z = cvt_pk_bf16(b[0], b[1]); w.w = cvt_pk_bf16(b[2], b[3]); return w; }
;     __device__ __forceinline__ void operator()(const f32x4 (&acc)[2][2][4][2], const Unit& u, int wr, int wc, int fr, int fq) const {
;         const int row0 = u.pm * BM + wr * 64 + fr, col0 = u.pn * BM + wc * 32 + 8 * fq;
; #pragma unroll
;         for (int ai = 0; ai < 2; ++ai) {
;             u32x4 xw[4][2]; float rms[4];
; #pragma unroll
;             for (int m = 0; m < 4; ++m) { const int row = row0 + ai * HALF + m * 16; rms[m] = rms1[row];
; #pragma unroll
;                 for (int bj = 0; bj < 2; ++bj) xw[m][bj] = *(const u32x4*)(XB + (size_t)row * 1024 + col0 + bj * HALF); }
; #pragma unroll
;             for (int m = 0; m < 4; ++m) {
;                 const int row = row0 + ai * HALF + m * 16;
;                 float ss = 0.f; const float r = rms[m];
; #pragma unroll
;                 for (int bj = 0; bj < 2; ++bj) { const int col = col0 + bj * HALF; const u32x4 w = xw[m][bj];
;                     const f32x4 a = (f32x4){__builtin_bit_cast(float, w.x << 16), __builtin_bit_cast(float, w.x & 0xffff0000u), __builtin_bit_cast(float, w.y << 16), __builtin_bit_cast(float, w.y & 0xffff0000u)} * r + acc[ai][bj][m][0],
;                                 b = (f32x4){__builtin_bit_cast(float, w.z << 16), __builtin_bit_cast(float, w.z & 0xffff0000u), __builtin_bit_cast(float, w.w << 16), __builtin_bit_cast(float, w.w & 0xffff0000u)} * r + acc[ai][bj][m][1];
;                     ss += dot4(a) + dot4(b);
;                     store16_wt(X1B + (size_t)row * 1024 + col, pack8(a, b)); }
;                 ss += __shfl_xor(ss, 16); ss += __shfl_xor(ss, 32);
;                 if (fq == 0) __hip_atomic_fetch_add(RSS + row, ss, __ATOMIC_RELAXED, __HIP_MEMORY_SCOPE_AGENT);
.LBB0_770:
	s_lshl_b32 s2, s20, 8
	s_add_i32 s2, s2, s33
	v_mbcnt_lo_u32_b32 v165, -1, 0
	v_mbcnt_hi_u32_b32 v165, -1, v165
	s_nop 0
	v_and_or_b32 v158, v165, 15, s2
	s_lshl_b32 s2, s8, 8
	v_ashrrev_i32_e32 v130, 1, v165
	s_or_b32 s2, s2, s35
	v_and_b32_e32 v130, -8, v130
	v_add_u32_e32 v154, s2, v130
	v_ashrrev_i32_e32 v155, 31, v154
	v_lshlrev_b64 v[188:189], 1, v[154:155]
	v_ashrrev_i32_e32 v159, 31, v158
	v_lshl_add_u64 v[156:157], s[16:17], 0, v[188:189]
	v_lshlrev_b64 v[190:191], 11, v[158:159]
	v_lshl_add_u64 v[130:131], v[156:157], 0, v[190:191]
	v_lshl_add_u64 v[160:161], v[158:159], 2, s[14:15]
	global_load_dwordx4 v[180:183], v[130:131], off
	global_load_dwordx4 v[184:187], v[130:131], off offset:256
	global_load_dword v192, v[160:161], off
	v_or_b32_e32 v174, 16, v158
	v_or_b32_e32 v168, 32, v158
	v_or_b32_e32 v162, 48, v158
	v_ashrrev_i32_e32 v175, 31, v174
	v_ashrrev_i32_e32 v169, 31, v168
	v_ashrrev_i32_e32 v163, 31, v162
	v_lshlrev_b64 v[178:179], 11, v[174:175]
	v_lshlrev_b64 v[172:173], 11, v[168:169]
	v_lshl_add_u64 v[130:131], v[174:175], 2, s[14:15]
	v_lshl_add_u64 v[132:133], v[168:169], 2, s[14:15]
	v_lshl_add_u64 v[134:135], v[162:163], 2, s[14:15]
	v_lshlrev_b64 v[166:167], 11, v[162:163]
	v_lshl_add_u64 v[136:137], v[156:157], 0, v[178:179]
	v_lshl_add_u64 v[138:139], v[156:157], 0, v[172:173]
	v_lshl_add_u64 v[194:195], v[156:157], 0, v[166:167]
	global_load_dword v176, v[130:131], off
	global_load_dwordx4 v[150:153], v[136:137], off
	global_load_dwordx4 v[146:149], v[136:137], off offset:256
	global_load_dword v170, v[132:133], off
	global_load_dwordx4 v[142:145], v[138:139], off
	s_nop 0
	global_load_dwordx4 v[138:141], v[138:139], off offset:256
	s_nop 0
	global_load_dword v164, v[134:135], off
	s_nop 0
	global_load_dwordx4 v[134:137], v[194:195], off
	global_load_dwordx4 v[130:133], v[194:195], off offset:256
	v_lshl_add_u64 v[190:191], s[12:13], 0, v[190:191]
	v_lshl_add_u64 v[188:189], v[190:191], 0, v[188:189]
	v_cmp_gt_u32_e32 vcc, 16, v165
	s_mov_b64 s[14:15], 0x100
	v_add_u32_e32 v250, 0x80, v158
	v_ashrrev_i32_e32 v251, 31, v250
	v_lshlrev_b64 v[252:253], 11, v[250:251]
	v_lshl_add_u64 v[246:247], v[156:157], 0, v[252:253]
	global_load_dwordx4 v[200:203], v[246:247], off
	global_load_dwordx4 v[204:207], v[246:247], off offset:256
	global_load_dword v236, v[160:161], off offset:512
	v_add_u32_e32 v250, 0x90, v158
	v_ashrrev_i32_e32 v251, 31, v250
	v_lshlrev_b64 v[252:253], 11, v[250:251]
	v_lshl_add_u64 v[246:247], v[156:157], 0, v[252:253]
	global_load_dwordx4 v[208:211], v[246:247], off
	global_load_dwordx4 v[212:215], v[246:247], off offset:256
	global_load_dword v238, v[160:161], off offset:576
	v_add_u32_e32 v250, 0xa0, v158
	v_ashrrev_i32_e32 v251, 31, v250
	v_lshlrev_b64 v[252:253], 11, v[250:251]
	v_lshl_add_u64 v[246:247], v[156:157], 0, v[252:253]
	global_load_dwordx4 v[216:219], v[246:247], off
	global_load_dwordx4 v[220:223], v[246:247], off offset:256
	global_load_dword v240, v[160:161], off offset:640
	v_add_u32_e32 v250, 0xb0, v158
	v_ashrrev_i32_e32 v251, 31, v250
	v_lshlrev_b64 v[252:253], 11, v[250:251]
	v_lshl_add_u64 v[246:247], v[156:157], 0, v[252:253]
	global_load_dwordx4 v[224:227], v[246:247], off
	global_load_dwordx4 v[232:235], v[246:247], off offset:256
	global_load_dword v244, v[160:161], off offset:704
	s_waitcnt vmcnt(0)
	v_lshlrev_b32_e32 v190, 16, v180
	v_and_b32_e32 v191, 0xffff0000, v180
	v_lshlrev_b32_e32 v180, 16, v181
	v_and_b32_e32 v181, 0xffff0000, v181
	v_lshlrev_b32_e32 v194, 16, v182
	v_and_b32_e32 v195, 0xffff0000, v182
	v_lshlrev_b32_e32 v182, 16, v183
	v_and_b32_e32 v183, 0xffff0000, v183
	v_lshlrev_b32_e32 v196, 16, v184
	v_and_b32_e32 v197, 0xffff0000, v184
	v_lshlrev_b32_e32 v184, 16, v185
	v_and_b32_e32 v185, 0xffff0000, v185
	v_lshlrev_b32_e32 v198, 16, v186
	v_and_b32_e32 v199, 0xffff0000, v186
	v_lshlrev_b32_e32 v186, 16, v187
	v_and_b32_e32 v187, 0xffff0000, v187
	v_pk_fma_f32 v[128:129], v[192:193], v[180:181], v[128:129] op_sel_hi:[0,1,1]
	v_pk_fma_f32 v[126:127], v[192:193], v[190:191], v[126:127] op_sel_hi:[0,1,1]
	v_pk_fma_f32 v[124:125], v[192:193], v[182:183], v[124:125] op_sel_hi:[0,1,1]
	v_pk_fma_f32 v[122:123], v[192:193], v[194:195], v[122:123] op_sel_hi:[0,1,1]
	v_pk_fma_f32 v[120:121], v[192:193], v[184:185], v[120:121] op_sel_hi:[0,1,1]
	v_pk_fma_f32 v[118:119], v[192:193], v[196:197], v[118:119] op_sel_hi:[0,1,1]
	v_pk_fma_f32 v[180:181], v[192:193], v[186:187], v[116:117] op_sel_hi:[0,1,1]
	v_pk_fma_f32 v[182:183], v[192:193], v[198:199], v[114:115] op_sel_hi:[0,1,1]
	v_mul_f32_e32 v165, v127, v127
	v_mul_f32_e32 v171, v129, v129
	v_mul_f32_e32 v177, v123, v123
	v_mul_f32_e32 v184, v125, v125
	v_cvt_pk_bf16_f32 v114, v126, v127
	v_cvt_pk_bf16_f32 v115, v128, v129
	v_cvt_pk_bf16_f32 v116, v122, v123
	v_cvt_pk_bf16_f32 v117, v124, v125
	v_mul_f32_e32 v123, v119, v119
	v_mul_f32_e32 v125, v121, v121
	v_mul_f32_e32 v127, v183, v183
	v_mul_f32_e32 v129, v181, v181
	v_fmac_f32_e32 v165, v126, v126
	v_fmac_f32_e32 v171, v128, v128
	v_fmac_f32_e32 v177, v122, v122
	v_fmac_f32_e32 v184, v124, v124
	global_store_dwordx4 v[188:189], v[114:117], off sc1
	s_nop 1
	v_fmac_f32_e32 v123, v118, v118
	v_fmac_f32_e32 v125, v120, v120
	v_fmac_f32_e32 v127, v182, v182
	v_add_f32_e32 v114, v165, v171
	v_add_f32_e32 v115, v177, v184
	v_fmac_f32_e32 v129, v180, v180
	v_add_f32_e32 v116, v123, v125
	v_add_f32_e32 v114, v114, v115
	v_add_f32_e32 v115, v127, v129
	v_add_f32_e32 v115, v116, v115
	v_and_b32_e32 v116, 64, v1
	v_add_f32_e32 v115, v114, v115
	v_xor_b32_e32 v114, 16, v1
	v_add_u32_e32 v117, 64, v116
	v_cmp_lt_i32_e64 s[8:9], v114, v117
	v_lshl_add_u64 v[122:123], v[188:189], 0, s[14:15]
	v_cvt_pk_bf16_f32 v118, v118, v119
	v_cndmask_b32_e64 v114, v1, v114, s[8:9]
	v_lshlrev_b32_e32 v114, 2, v114
	v_mov_b32_e32 v116, v115
	s_nop 1
	v_permlane16_swap_b32_e32 v116, v115
	v_cvt_pk_bf16_f32 v119, v120, v121
	v_cvt_pk_bf16_f32 v120, v182, v183
	v_cvt_pk_bf16_f32 v121, v180, v181
	global_store_dwordx4 v[122:123], v[118:121], off sc1
	s_nop 1
	s_waitcnt lgkmcnt(0)
	v_add_f32_e32 v116, v115, v116
	v_xor_b32_e32 v115, 32, v1
	v_cmp_lt_i32_e64 s[8:9], v115, v117
	s_nop 1
	v_cndmask_b32_e64 v115, v1, v115, s[8:9]
	v_lshlrev_b32_e32 v115, 2, v115
	v_mov_b32_e32 v117, v116
	s_nop 1
	v_permlane32_swap_b32_e32 v117, v116
	s_and_saveexec_b64 s[8:9], vcc
	s_cbranch_execz .LBB0_772
	v_lshl_add_u64 v[118:119], v[158:159], 2, s[10:11]
	s_waitcnt lgkmcnt(0)
	v_add_f32_e32 v116, v116, v117
	global_atomic_add_f32 v[118:119], v116, off
; __device__ __forceinline__ float dot4(f32x4 a) { return (a[0] * a[0] + a[1] * a[1]) + (a[2] * a[2] + a[3] * a[3]); }
; __device__ __forceinline__ void store16_wt(void* p, u32x4 v) { asm volatile("global_store_dwordx4 %0, %1, off sc1\n\ts_nop 1" :: "v"(p), "v"(v) : "memory"); }
; __device__ __forceinline__ u32x4 pack8(f32x4 a, f32x4 b) { u32x4 w; w.x = cvt_pk_bf16(a[0], a[1]); w.y = cvt_pk_bf16(a[2], a[3]); w.z = cvt_pk_bf16(b[0], b[1]); w.w = cvt_pk_bf16(b[2], b[3]); return w; }
;     __device__ __forceinline__ void operator()(const f32x4 (&acc)[2][2][4][2], const Unit& u, int wr, int wc, int fr, int fq) const {
;     ...
;         for (int ai = 0; ai < 2; ++ai) {
;             u32x4 xw[4][2]; float rms[4];
; #pragma unroll
;             for (int m = 0; m < 4; ++m) { const int row = row0 + ai * HALF + m * 16; rms[m] = rms1[row];
; #pragma unroll
;                 for (int bj = 0; bj < 2; ++bj) xw[m][bj] = *(const u32x4*)(XB + (size_t)row * 1024 + col0 + bj * HALF); }
; #pragma unroll
;             for (int m = 0; m < 4; ++m) {
;                 const int row = row0 + ai * HALF + m * 16;
;                 float ss = 0.f; const float r = rms[m];
; #pragma unroll
;                 for (int bj = 0; bj < 2; ++bj) { const int col = col0 + bj * HALF; const u32x4 w = xw[m][bj];
;                     const f32x4 a = (f32x4){__builtin_bit_cast(float, w.x << 16), __builtin_bit_cast(float, w.x & 0xffff0000u), __builtin_bit_cast(float, w.y << 16), __builtin_bit_cast(float, w.y & 0xffff0000u)} * r + acc[ai][bj][m][0],
;                                 b = (f32x4){__builtin_bit_cast(float, w.z << 16), __builtin_bit_cast(float, w.z & 0xffff0000u), __builtin_bit_cast(float, w.w << 16), __builtin_bit_cast(float, w.w & 0xffff0000u)} * r + acc[ai][bj][m][1];
;                     ss += dot4(a) + dot4(b);
;                     store16_wt(X1B + (size_t)row * 1024 + col, pack8(a, b)); }
;                 ss += __shfl_xor(ss, 16); ss += __shfl_xor(ss, 32);
;                 if (fq == 0) __hip_atomic_fetch_add(RSS + row, ss, __ATOMIC_RELAXED, __HIP_MEMORY_SCOPE_AGENT);
;             }
.LBB0_772:
	s_or_b64 exec, exec, s[8:9]
	v_lshlrev_b32_e32 v116, 16, v150
	s_waitcnt lgkmcnt(0)
	v_and_b32_e32 v117, 0xffff0000, v150
	v_lshlrev_b32_e32 v118, 16, v151
	v_and_b32_e32 v119, 0xffff0000, v151
	v_pk_fma_f32 v[112:113], v[176:177], v[118:119], v[112:113] op_sel_hi:[0,1,1]
	v_pk_fma_f32 v[110:111], v[176:177], v[116:117], v[110:111] op_sel_hi:[0,1,1]
	v_lshlrev_b32_e32 v116, 16, v152
	v_and_b32_e32 v117, 0xffff0000, v152
	v_lshlrev_b32_e32 v118, 16, v153
	v_and_b32_e32 v119, 0xffff0000, v153
	v_pk_fma_f32 v[118:119], v[176:177], v[118:119], v[108:109] op_sel_hi:[0,1,1]
	v_pk_fma_f32 v[108:109], v[176:177], v[116:117], v[106:107] op_sel_hi:[0,1,1]
	v_mul_f32_e32 v106, v111, v111
	v_mul_f32_e32 v107, v113, v113
	v_fmac_f32_e32 v106, v110, v110
	v_fmac_f32_e32 v107, v112, v112
	v_add_f32_e32 v106, v106, v107
	v_mul_f32_e32 v107, v109, v109
	v_mul_f32_e32 v116, v119, v119
	v_fmac_f32_e32 v107, v108, v108
	v_fmac_f32_e32 v116, v118, v118
	v_add_f32_e32 v107, v107, v116
	v_add_f32_e32 v120, v106, v107
	v_lshl_add_u64 v[106:107], s[12:13], 0, v[178:179]
	v_lshl_add_u64 v[116:117], v[154:155], 1, v[106:107]
	v_cvt_pk_bf16_f32 v106, v110, v111
	v_cvt_pk_bf16_f32 v107, v112, v113
	v_cvt_pk_bf16_f32 v108, v108, v109
	v_cvt_pk_bf16_f32 v109, v118, v119
	global_store_dwordx4 v[116:117], v[106:109], off sc1
	s_nop 1
	v_lshlrev_b32_e32 v106, 16, v146
	v_and_b32_e32 v107, 0xffff0000, v146
	v_lshlrev_b32_e32 v108, 16, v147
	v_and_b32_e32 v109, 0xffff0000, v147
	v_pk_fma_f32 v[104:105], v[176:177], v[108:109], v[104:105] op_sel_hi:[0,1,1]
	v_pk_fma_f32 v[102:103], v[176:177], v[106:107], v[102:103] op_sel_hi:[0,1,1]
	v_lshlrev_b32_e32 v108, 16, v149
	v_and_b32_e32 v109, 0xffff0000, v149
	v_lshlrev_b32_e32 v106, 16, v148
	v_and_b32_e32 v107, 0xffff0000, v148
	v_pk_fma_f32 v[108:109], v[176:177], v[108:109], v[100:101] op_sel_hi:[0,1,1]
	v_mul_f32_e32 v100, v103, v103
	v_mul_f32_e32 v101, v105, v105
	v_pk_fma_f32 v[98:99], v[176:177], v[106:107], v[98:99] op_sel_hi:[0,1,1]
	v_fmac_f32_e32 v100, v102, v102
	v_fmac_f32_e32 v101, v104, v104
	v_add_f32_e32 v100, v100, v101
	v_mul_f32_e32 v101, v99, v99
	v_mul_f32_e32 v106, v109, v109
	v_fmac_f32_e32 v101, v98, v98
	v_fmac_f32_e32 v106, v108, v108
	v_add_f32_e32 v101, v101, v106
	v_add_f32_e32 v100, v100, v101
	v_add_f32_e32 v110, v120, v100
	v_mov_b32_e32 v111, v110
	s_nop 1
	v_permlane16_swap_b32_e32 v111, v110
	v_cvt_pk_bf16_f32 v100, v102, v103
	v_cvt_pk_bf16_f32 v102, v98, v99
	v_lshl_add_u64 v[106:107], v[116:117], 0, s[14:15]
	v_cvt_pk_bf16_f32 v101, v104, v105
	s_waitcnt lgkmcnt(0)
	v_add_f32_e32 v98, v110, v111
	v_mov_b32_e32 v99, v98
	s_nop 1
	v_permlane32_swap_b32_e32 v99, v98
	v_cvt_pk_bf16_f32 v103, v108, v109
	global_store_dwordx4 v[106:107], v[100:103], off sc1
	s_nop 1
	s_and_saveexec_b64 s[8:9], vcc
	s_cbranch_execz .LBB0_774
	v_lshl_add_u64 v[100:101], v[174:175], 2, s[10:11]
	s_waitcnt lgkmcnt(0)
	v_add_f32_e32 v98, v98, v99
	global_atomic_add_f32 v[100:101], v98, off
.LBB0_774:
	s_or_b64 exec, exec, s[8:9]
	v_lshlrev_b32_e32 v98, 16, v142
	s_waitcnt lgkmcnt(0)
	v_and_b32_e32 v99, 0xffff0000, v142
	v_lshlrev_b32_e32 v100, 16, v143
	v_and_b32_e32 v101, 0xffff0000, v143
	v_pk_fma_f32 v[96:97], v[170:171], v[100:101], v[96:97] op_sel_hi:[0,1,1]
	v_pk_fma_f32 v[94:95], v[170:171], v[98:99], v[94:95] op_sel_hi:[0,1,1]
	v_lshlrev_b32_e32 v98, 16, v144
	v_and_b32_e32 v99, 0xffff0000, v144
	v_lshlrev_b32_e32 v100, 16, v145
	v_and_b32_e32 v101, 0xffff0000, v145
	v_pk_fma_f32 v[100:101], v[170:171], v[100:101], v[92:93] op_sel_hi:[0,1,1]
	v_pk_fma_f32 v[92:93], v[170:171], v[98:99], v[90:91] op_sel_hi:[0,1,1]
	v_mul_f32_e32 v90, v95, v95
	v_mul_f32_e32 v91, v97, v97
	v_fmac_f32_e32 v90, v94, v94
	v_fmac_f32_e32 v91, v96, v96
	v_add_f32_e32 v90, v90, v91
	v_mul_f32_e32 v91, v93, v93
	v_mul_f32_e32 v98, v101, v101
	v_fmac_f32_e32 v91, v92, v92
	v_fmac_f32_e32 v98, v100, v100
	v_add_f32_e32 v91, v91, v98
	v_add_f32_e32 v102, v90, v91
	v_lshl_add_u64 v[90:91], s[12:13], 0, v[172:173]
	v_lshl_add_u64 v[98:99], v[154:155], 1, v[90:91]
	v_cvt_pk_bf16_f32 v90, v94, v95
	v_cvt_pk_bf16_f32 v91, v96, v97
	v_cvt_pk_bf16_f32 v92, v92, v93
	v_cvt_pk_bf16_f32 v93, v100, v101
	global_store_dwordx4 v[98:99], v[90:93], off sc1
	s_nop 1
	v_lshlrev_b32_e32 v90, 16, v138
	v_and_b32_e32 v91, 0xffff0000, v138
	v_lshlrev_b32_e32 v92, 16, v139
	v_and_b32_e32 v93, 0xffff0000, v139
	v_pk_fma_f32 v[88:89], v[170:171], v[92:93], v[88:89] op_sel_hi:[0,1,1]
	v_pk_fma_f32 v[86:87], v[170:171], v[90:91], v[86:87] op_sel_hi:[0,1,1]
	v_lshlrev_b32_e32 v92, 16, v141
	v_and_b32_e32 v93, 0xffff0000, v141
	v_lshlrev_b32_e32 v90, 16, v140
	v_and_b32_e32 v91, 0xffff0000, v140
	v_pk_fma_f32 v[92:93], v[170:171], v[92:93], v[84:85] op_sel_hi:[0,1,1]
	v_mul_f32_e32 v84, v87, v87
	v_mul_f32_e32 v85, v89, v89
	v_pk_fma_f32 v[82:83], v[170:171], v[90:91], v[82:83] op_sel_hi:[0,1,1]
	v_fmac_f32_e32 v84, v86, v86
	v_fmac_f32_e32 v85, v88, v88
	v_add_f32_e32 v84, v84, v85
	v_mul_f32_e32 v85, v83, v83
	v_mul_f32_e32 v90, v93, v93
	v_fmac_f32_e32 v85, v82, v82
	v_fmac_f32_e32 v90, v92, v92
	v_add_f32_e32 v85, v85, v90
	v_add_f32_e32 v84, v84, v85
	v_add_f32_e32 v94, v102, v84
	v_mov_b32_e32 v95, v94
	s_nop 1
	v_permlane16_swap_b32_e32 v95, v94
	v_cvt_pk_bf16_f32 v84, v86, v87
	v_cvt_pk_bf16_f32 v86, v82, v83
	s_mov_b64 s[8:9], 0x100
	v_lshl_add_u64 v[90:91], v[98:99], 0, s[8:9]
	s_waitcnt lgkmcnt(0)
	v_add_f32_e32 v82, v94, v95
	v_mov_b32_e32 v83, v82
	s_nop 1
	v_permlane32_swap_b32_e32 v83, v82
	v_cvt_pk_bf16_f32 v85, v88, v89
	v_cvt_pk_bf16_f32 v87, v92, v93
	global_store_dwordx4 v[90:91], v[84:87], off sc1
	s_nop 1
	s_and_saveexec_b64 s[14:15], vcc
	s_cbranch_execz .LBB0_776
	v_lshl_add_u64 v[84:85], v[168:169], 2, s[10:11]
	s_waitcnt lgkmcnt(0)
	v_add_f32_e32 v82, v82, v83
	global_atomic_add_f32 v[84:85], v82, off
; __device__ __forceinline__ float dot4(f32x4 a) { return (a[0] * a[0] + a[1] * a[1]) + (a[2] * a[2] + a[3] * a[3]); }
; __device__ __forceinline__ void store16_wt(void* p, u32x4 v) { asm volatile("global_store_dwordx4 %0, %1, off sc1\n\ts_nop 1" :: "v"(p), "v"(v) : "memory"); }
; __device__ __forceinline__ u32x4 pack8(f32x4 a, f32x4 b) { u32x4 w; w.x = cvt_pk_bf16(a[0], a[1]); w.y = cvt_pk_bf16(a[2], a[3]); w.z = cvt_pk_bf16(b[0], b[1]); w.w = cvt_pk_bf16(b[2], b[3]); return w; }
;     __device__ __forceinline__ void operator()(const f32x4 (&acc)[2][2][4][2], const Unit& u, int wr, int wc, int fr, int fq) const {
;     ...
;         for (int ai = 0; ai < 2; ++ai) {
;             u32x4 xw[4][2]; float rms[4];
; #pragma unroll
;             for (int m = 0; m < 4; ++m) { const int row = row0 + ai * HALF + m * 16; rms[m] = rms1[row];
; #pragma unroll
;                 for (int bj = 0; bj < 2; ++bj) xw[m][bj] = *(const u32x4*)(XB + (size_t)row * 1024 + col0 + bj * HALF); }
; #pragma unroll
;             for (int m = 0; m < 4; ++m) {
;                 const int row = row0 + ai * HALF + m * 16;
;                 float ss = 0.f; const float r = rms[m];
; #pragma unroll
;                 for (int bj = 0; bj < 2; ++bj) { const int col = col0 + bj * HALF; const u32x4 w = xw[m][bj];
;                     const f32x4 a = (f32x4){__builtin_bit_cast(float, w.x << 16), __builtin_bit_cast(float, w.x & 0xffff0000u), __builtin_bit_cast(float, w.y << 16), __builtin_bit_cast(float, w.y & 0xffff0000u)} * r + acc[ai][bj][m][0],
;                                 b = (f32x4){__builtin_bit_cast(float, w.z << 16), __builtin_bit_cast(float, w.z & 0xffff0000u), __builtin_bit_cast(float, w.w << 16), __builtin_bit_cast(float, w.w & 0xffff0000u)} * r + acc[ai][bj][m][1];
;                     ss += dot4(a) + dot4(b);
;                     store16_wt(X1B + (size_t)row * 1024 + col, pack8(a, b)); }
;                 ss += __shfl_xor(ss, 16); ss += __shfl_xor(ss, 32);
;                 if (fq == 0) __hip_atomic_fetch_add(RSS + row, ss, __ATOMIC_RELAXED, __HIP_MEMORY_SCOPE_AGENT);
;             }
.LBB0_776:
	s_or_b64 exec, exec, s[14:15]
	v_lshlrev_b32_e32 v82, 16, v134
	s_waitcnt lgkmcnt(0)
	v_and_b32_e32 v83, 0xffff0000, v134
	v_lshlrev_b32_e32 v84, 16, v135
	v_and_b32_e32 v85, 0xffff0000, v135
	v_pk_fma_f32 v[80:81], v[164:165], v[84:85], v[80:81] op_sel_hi:[0,1,1]
	v_pk_fma_f32 v[78:79], v[164:165], v[82:83], v[78:79] op_sel_hi:[0,1,1]
	v_lshlrev_b32_e32 v82, 16, v136
	v_and_b32_e32 v83, 0xffff0000, v136
	v_lshlrev_b32_e32 v84, 16, v137
	v_and_b32_e32 v85, 0xffff0000, v137
	v_pk_fma_f32 v[84:85], v[164:165], v[84:85], v[76:77] op_sel_hi:[0,1,1]
	v_pk_fma_f32 v[76:77], v[164:165], v[82:83], v[74:75] op_sel_hi:[0,1,1]
	v_mul_f32_e32 v74, v79, v79
	v_mul_f32_e32 v75, v81, v81
	v_fmac_f32_e32 v74, v78, v78
	v_fmac_f32_e32 v75, v80, v80
	v_add_f32_e32 v74, v74, v75
	v_mul_f32_e32 v75, v77, v77
	v_mul_f32_e32 v82, v85, v85
	v_fmac_f32_e32 v75, v76, v76
	v_fmac_f32_e32 v82, v84, v84
	v_add_f32_e32 v75, v75, v82
	v_add_f32_e32 v86, v74, v75
	v_lshl_add_u64 v[74:75], s[12:13], 0, v[166:167]
	v_lshl_add_u64 v[82:83], v[154:155], 1, v[74:75]
	v_cvt_pk_bf16_f32 v74, v78, v79
	v_cvt_pk_bf16_f32 v75, v80, v81
	v_cvt_pk_bf16_f32 v76, v76, v77
	v_cvt_pk_bf16_f32 v77, v84, v85
	global_store_dwordx4 v[82:83], v[74:77], off sc1
	s_nop 1
	v_lshlrev_b32_e32 v74, 16, v130
	v_and_b32_e32 v75, 0xffff0000, v130
	v_lshlrev_b32_e32 v76, 16, v131
	v_and_b32_e32 v77, 0xffff0000, v131
	v_pk_fma_f32 v[72:73], v[164:165], v[76:77], v[72:73] op_sel_hi:[0,1,1]
	v_pk_fma_f32 v[70:71], v[164:165], v[74:75], v[70:71] op_sel_hi:[0,1,1]
	v_lshlrev_b32_e32 v76, 16, v133
	v_and_b32_e32 v77, 0xffff0000, v133
	v_lshlrev_b32_e32 v74, 16, v132
	v_and_b32_e32 v75, 0xffff0000, v132
	v_pk_fma_f32 v[76:77], v[164:165], v[76:77], v[68:69] op_sel_hi:[0,1,1]
	v_mul_f32_e32 v68, v71, v71
	v_mul_f32_e32 v69, v73, v73
	v_pk_fma_f32 v[66:67], v[164:165], v[74:75], v[66:67] op_sel_hi:[0,1,1]
	v_fmac_f32_e32 v68, v70, v70
	v_fmac_f32_e32 v69, v72, v72
	v_add_f32_e32 v68, v68, v69
	v_mul_f32_e32 v69, v67, v67
	v_mul_f32_e32 v74, v77, v77
	v_fmac_f32_e32 v69, v66, v66
	v_fmac_f32_e32 v74, v76, v76
	v_add_f32_e32 v69, v69, v74
	v_add_f32_e32 v68, v68, v69
	v_add_f32_e32 v78, v86, v68
	v_mov_b32_e32 v79, v78
	s_nop 1
	v_permlane16_swap_b32_e32 v79, v78
	v_cvt_pk_bf16_f32 v68, v70, v71
	v_cvt_pk_bf16_f32 v70, v66, v67
	v_lshl_add_u64 v[74:75], v[82:83], 0, s[8:9]
	v_cvt_pk_bf16_f32 v69, v72, v73
	s_waitcnt lgkmcnt(0)
	v_add_f32_e32 v66, v78, v79
	v_mov_b32_e32 v67, v66
	s_nop 1
	v_permlane32_swap_b32_e32 v67, v66
	v_cvt_pk_bf16_f32 v71, v76, v77
	global_store_dwordx4 v[74:75], v[68:71], off sc1
	s_nop 1
	s_and_saveexec_b64 s[8:9], vcc
	s_cbranch_execz .LBB0_778
	v_lshl_add_u64 v[68:69], v[162:163], 2, s[10:11]
	s_waitcnt lgkmcnt(0)
	v_add_f32_e32 v66, v66, v67
	global_atomic_add_f32 v[68:69], v66, off
.LBB0_778:
	s_or_b64 exec, exec, s[8:9]
	v_add_u32_e32 v108, 0x80, v158
	v_ashrrev_i32_e32 v109, 31, v108
	v_lshlrev_b64 v[120:121], 11, v[108:109]
	s_waitcnt lgkmcnt(0)
	v_add_u32_e32 v102, 0x90, v158
	v_add_u32_e32 v96, 0xa0, v158
	v_add_u32_e32 v90, 0xb0, v158
	v_ashrrev_i32_e32 v103, 31, v102
	v_ashrrev_i32_e32 v97, 31, v96
	v_ashrrev_i32_e32 v91, 31, v90
	v_lshlrev_b64 v[106:107], 11, v[102:103]
	v_lshlrev_b64 v[100:101], 11, v[96:97]
	v_lshlrev_b64 v[94:95], 11, v[90:91]
	v_lshl_add_u64 v[124:125], v[156:157], 0, v[94:95]
	s_nop 0
	v_lshl_add_u64 v[120:121], s[12:13], 0, v[120:121]
	v_lshl_add_u64 v[120:121], v[154:155], 1, v[120:121]
	s_mov_b64 s[8:9], 0x100
	v_lshlrev_b32_e32 v124, 16, v200
	v_and_b32_e32 v125, 0xffff0000, v200
	v_lshlrev_b32_e32 v200, 16, v201
	v_and_b32_e32 v201, 0xffff0000, v201
	v_lshlrev_b32_e32 v126, 16, v202
	v_and_b32_e32 v127, 0xffff0000, v202
	v_lshlrev_b32_e32 v202, 16, v203
	v_and_b32_e32 v203, 0xffff0000, v203
	v_lshlrev_b32_e32 v128, 16, v204
	v_and_b32_e32 v129, 0xffff0000, v204
	v_lshlrev_b32_e32 v204, 16, v205
	v_and_b32_e32 v205, 0xffff0000, v205
	v_lshlrev_b32_e32 v130, 16, v206
	v_and_b32_e32 v131, 0xffff0000, v206
	v_lshlrev_b32_e32 v206, 16, v207
	v_and_b32_e32 v207, 0xffff0000, v207
	v_pk_fma_f32 v[64:65], v[236:237], v[200:201], v[64:65] op_sel_hi:[0,1,1]
	v_pk_fma_f32 v[62:63], v[236:237], v[124:125], v[62:63] op_sel_hi:[0,1,1]
	v_pk_fma_f32 v[60:61], v[236:237], v[202:203], v[60:61] op_sel_hi:[0,1,1]
	v_pk_fma_f32 v[58:59], v[236:237], v[126:127], v[58:59] op_sel_hi:[0,1,1]
	v_pk_fma_f32 v[56:57], v[236:237], v[204:205], v[56:57] op_sel_hi:[0,1,1]
	v_pk_fma_f32 v[54:55], v[236:237], v[128:129], v[54:55] op_sel_hi:[0,1,1]
	v_pk_fma_f32 v[200:201], v[236:237], v[206:207], v[52:53] op_sel_hi:[0,1,1]
	v_pk_fma_f32 v[202:203], v[236:237], v[130:131], v[50:51] op_sel_hi:[0,1,1]
	v_mul_f32_e32 v245, v63, v63
	v_mul_f32_e32 v241, v65, v65
	v_mul_f32_e32 v239, v59, v59
	v_mul_f32_e32 v204, v61, v61
	v_cvt_pk_bf16_f32 v50, v62, v63
	v_cvt_pk_bf16_f32 v51, v64, v65
	v_cvt_pk_bf16_f32 v52, v58, v59
	v_cvt_pk_bf16_f32 v53, v60, v61
	v_mul_f32_e32 v59, v55, v55
	v_mul_f32_e32 v61, v57, v57
	v_mul_f32_e32 v63, v203, v203
	v_mul_f32_e32 v65, v201, v201
	v_fmac_f32_e32 v245, v62, v62
	v_fmac_f32_e32 v241, v64, v64
	v_fmac_f32_e32 v239, v58, v58
	v_fmac_f32_e32 v204, v60, v60
	v_fmac_f32_e32 v59, v54, v54
	v_fmac_f32_e32 v61, v56, v56
	v_fmac_f32_e32 v63, v202, v202
	v_fmac_f32_e32 v65, v200, v200
	global_store_dwordx4 v[120:121], v[50:53], off sc1
	s_nop 1
	v_add_f32_e32 v50, v245, v241
	v_add_f32_e32 v51, v239, v204
	v_add_f32_e32 v52, v59, v61
	v_add_f32_e32 v53, v63, v65
	v_add_f32_e32 v50, v50, v51
	v_add_f32_e32 v51, v52, v53
	v_add_f32_e32 v50, v50, v51
	v_mov_b32_e32 v51, v50
	s_nop 1
	v_permlane16_swap_b32_e32 v51, v50
	v_lshl_add_u64 v[58:59], v[120:121], 0, s[8:9]
	v_cvt_pk_bf16_f32 v52, v54, v55
	v_cvt_pk_bf16_f32 v53, v56, v57
	v_cvt_pk_bf16_f32 v54, v202, v203
	s_waitcnt lgkmcnt(0)
	v_add_f32_e32 v50, v50, v51
	v_mov_b32_e32 v51, v50
	s_nop 1
	v_permlane32_swap_b32_e32 v51, v50
	v_cvt_pk_bf16_f32 v55, v200, v201
	global_store_dwordx4 v[58:59], v[52:55], off sc1
	s_nop 1
	s_and_saveexec_b64 s[14:15], vcc
	s_cbranch_execz .LBB0_780
	v_lshl_add_u64 v[52:53], v[108:109], 2, s[10:11]
	s_waitcnt lgkmcnt(0)
	v_add_f32_e32 v50, v50, v51
	global_atomic_add_f32 v[52:53], v50, off
; __device__ __forceinline__ float dot4(f32x4 a) { return (a[0] * a[0] + a[1] * a[1]) + (a[2] * a[2] + a[3] * a[3]); }
; __device__ __forceinline__ void store16_wt(void* p, u32x4 v) { asm volatile("global_store_dwordx4 %0, %1, off sc1\n\ts_nop 1" :: "v"(p), "v"(v) : "memory"); }
; __device__ __forceinline__ u32x4 pack8(f32x4 a, f32x4 b) { u32x4 w; w.x = cvt_pk_bf16(a[0], a[1]); w.y = cvt_pk_bf16(a[2], a[3]); w.z = cvt_pk_bf16(b[0], b[1]); w.w = cvt_pk_bf16(b[2], b[3]); return w; }
;     __device__ __forceinline__ void operator()(const f32x4 (&acc)[2][2][4][2], const Unit& u, int wr, int wc, int fr, int fq) const {
;     ...
;         for (int ai = 0; ai < 2; ++ai) {
;             u32x4 xw[4][2]; float rms[4];
; #pragma unroll
;             for (int m = 0; m < 4; ++m) { const int row = row0 + ai * HALF + m * 16; rms[m] = rms1[row];
; #pragma unroll
;                 for (int bj = 0; bj < 2; ++bj) xw[m][bj] = *(const u32x4*)(XB + (size_t)row * 1024 + col0 + bj * HALF); }
; #pragma unroll
;             for (int m = 0; m < 4; ++m) {
;                 const int row = row0 + ai * HALF + m * 16;
;                 float ss = 0.f; const float r = rms[m];
; #pragma unroll
;                 for (int bj = 0; bj < 2; ++bj) { const int col = col0 + bj * HALF; const u32x4 w = xw[m][bj];
;                     const f32x4 a = (f32x4){__builtin_bit_cast(float, w.x << 16), __builtin_bit_cast(float, w.x & 0xffff0000u), __builtin_bit_cast(float, w.y << 16), __builtin_bit_cast(float, w.y & 0xffff0000u)} * r + acc[ai][bj][m][0],
;                                 b = (f32x4){__builtin_bit_cast(float, w.z << 16), __builtin_bit_cast(float, w.z & 0xffff0000u), __builtin_bit_cast(float, w.w << 16), __builtin_bit_cast(float, w.w & 0xffff0000u)} * r + acc[ai][bj][m][1];
;                     ss += dot4(a) + dot4(b);
;                     store16_wt(X1B + (size_t)row * 1024 + col, pack8(a, b)); }
;                 ss += __shfl_xor(ss, 16); ss += __shfl_xor(ss, 32);
;                 if (fq == 0) __hip_atomic_fetch_add(RSS + row, ss, __ATOMIC_RELAXED, __HIP_MEMORY_SCOPE_AGENT);
;             }
.LBB0_780:
	s_or_b64 exec, exec, s[14:15]
	v_lshlrev_b32_e32 v50, 16, v208
	s_waitcnt lgkmcnt(0)
	v_and_b32_e32 v51, 0xffff0000, v208
	v_lshlrev_b32_e32 v52, 16, v209
	v_and_b32_e32 v53, 0xffff0000, v209
	v_pk_fma_f32 v[48:49], v[238:239], v[52:53], v[48:49] op_sel_hi:[0,1,1]
	v_pk_fma_f32 v[46:47], v[238:239], v[50:51], v[46:47] op_sel_hi:[0,1,1]
	v_lshlrev_b32_e32 v50, 16, v210
	v_and_b32_e32 v51, 0xffff0000, v210
	v_lshlrev_b32_e32 v52, 16, v211
	v_and_b32_e32 v53, 0xffff0000, v211
	v_pk_fma_f32 v[52:53], v[238:239], v[52:53], v[44:45] op_sel_hi:[0,1,1]
	v_pk_fma_f32 v[44:45], v[238:239], v[50:51], v[42:43] op_sel_hi:[0,1,1]
	v_mul_f32_e32 v42, v47, v47
	v_mul_f32_e32 v43, v49, v49
	v_fmac_f32_e32 v42, v46, v46
	v_fmac_f32_e32 v43, v48, v48
	v_add_f32_e32 v42, v42, v43
	v_mul_f32_e32 v43, v45, v45
	v_mul_f32_e32 v50, v53, v53
	v_fmac_f32_e32 v43, v44, v44
	v_fmac_f32_e32 v50, v52, v52
	v_add_f32_e32 v43, v43, v50
	v_add_f32_e32 v54, v42, v43
	v_lshl_add_u64 v[42:43], s[12:13], 0, v[106:107]
	v_lshl_add_u64 v[50:51], v[154:155], 1, v[42:43]
	v_cvt_pk_bf16_f32 v42, v46, v47
	v_cvt_pk_bf16_f32 v43, v48, v49
	v_cvt_pk_bf16_f32 v44, v44, v45
	v_cvt_pk_bf16_f32 v45, v52, v53
	global_store_dwordx4 v[50:51], v[42:45], off sc1
	s_nop 1
	v_lshlrev_b32_e32 v42, 16, v212
	v_and_b32_e32 v43, 0xffff0000, v212
	v_lshlrev_b32_e32 v44, 16, v213
	v_and_b32_e32 v45, 0xffff0000, v213
	v_pk_fma_f32 v[40:41], v[238:239], v[44:45], v[40:41] op_sel_hi:[0,1,1]
	v_pk_fma_f32 v[38:39], v[238:239], v[42:43], v[38:39] op_sel_hi:[0,1,1]
	v_lshlrev_b32_e32 v44, 16, v215
	v_and_b32_e32 v45, 0xffff0000, v215
	v_lshlrev_b32_e32 v42, 16, v214
	v_and_b32_e32 v43, 0xffff0000, v214
	v_pk_fma_f32 v[44:45], v[238:239], v[44:45], v[36:37] op_sel_hi:[0,1,1]
	v_mul_f32_e32 v36, v39, v39
	v_mul_f32_e32 v37, v41, v41
	v_pk_fma_f32 v[34:35], v[238:239], v[42:43], v[34:35] op_sel_hi:[0,1,1]
	v_fmac_f32_e32 v36, v38, v38
	v_fmac_f32_e32 v37, v40, v40
	v_add_f32_e32 v36, v36, v37
	v_mul_f32_e32 v37, v35, v35
	v_mul_f32_e32 v42, v45, v45
	v_fmac_f32_e32 v37, v34, v34
	v_fmac_f32_e32 v42, v44, v44
	v_add_f32_e32 v37, v37, v42
	v_add_f32_e32 v36, v36, v37
	v_add_f32_e32 v46, v54, v36
	v_mov_b32_e32 v47, v46
	s_nop 1
	v_permlane16_swap_b32_e32 v47, v46
	v_cvt_pk_bf16_f32 v36, v38, v39
	v_cvt_pk_bf16_f32 v38, v34, v35
	v_lshl_add_u64 v[42:43], v[50:51], 0, s[8:9]
	v_cvt_pk_bf16_f32 v37, v40, v41
	s_waitcnt lgkmcnt(0)
	v_add_f32_e32 v34, v46, v47
	v_mov_b32_e32 v35, v34
	s_nop 1
	v_permlane32_swap_b32_e32 v35, v34
	v_cvt_pk_bf16_f32 v39, v44, v45
	global_store_dwordx4 v[42:43], v[36:39], off sc1
	s_nop 1
	s_and_saveexec_b64 s[8:9], vcc
	s_cbranch_execz .LBB0_782
	v_lshl_add_u64 v[36:37], v[102:103], 2, s[10:11]
	s_waitcnt lgkmcnt(0)
	v_add_f32_e32 v34, v34, v35
	global_atomic_add_f32 v[36:37], v34, off
; __device__ __forceinline__ float dot4(f32x4 a) { return (a[0] * a[0] + a[1] * a[1]) + (a[2] * a[2] + a[3] * a[3]); }
; __device__ __forceinline__ void store16_wt(void* p, u32x4 v) { asm volatile("global_store_dwordx4 %0, %1, off sc1\n\ts_nop 1" :: "v"(p), "v"(v) : "memory"); }
; __device__ __forceinline__ u32x4 pack8(f32x4 a, f32x4 b) { u32x4 w; w.x = cvt_pk_bf16(a[0], a[1]); w.y = cvt_pk_bf16(a[2], a[3]); w.z = cvt_pk_bf16(b[0], b[1]); w.w = cvt_pk_bf16(b[2], b[3]); return w; }
;     __device__ __forceinline__ void operator()(const f32x4 (&acc)[2][2][4][2], const Unit& u, int wr, int wc, int fr, int fq) const {
;     ...
;         for (int ai = 0; ai < 2; ++ai) {
;             u32x4 xw[4][2]; float rms[4];
; #pragma unroll
;             for (int m = 0; m < 4; ++m) { const int row = row0 + ai * HALF + m * 16; rms[m] = rms1[row];
; #pragma unroll
;                 for (int bj = 0; bj < 2; ++bj) xw[m][bj] = *(const u32x4*)(XB + (size_t)row * 1024 + col0 + bj * HALF); }
; #pragma unroll
;             for (int m = 0; m < 4; ++m) {
;                 const int row = row0 + ai * HALF + m * 16;
;                 float ss = 0.f; const float r = rms[m];
; #pragma unroll
;                 for (int bj = 0; bj < 2; ++bj) { const int col = col0 + bj * HALF; const u32x4 w = xw[m][bj];
;                     const f32x4 a = (f32x4){__builtin_bit_cast(float, w.x << 16), __builtin_bit_cast(float, w.x & 0xffff0000u), __builtin_bit_cast(float, w.y << 16), __builtin_bit_cast(float, w.y & 0xffff0000u)} * r + acc[ai][bj][m][0],
;                                 b = (f32x4){__builtin_bit_cast(float, w.z << 16), __builtin_bit_cast(float, w.z & 0xffff0000u), __builtin_bit_cast(float, w.w << 16), __builtin_bit_cast(float, w.w & 0xffff0000u)} * r + acc[ai][bj][m][1];
;                     ss += dot4(a) + dot4(b);
;                     store16_wt(X1B + (size_t)row * 1024 + col, pack8(a, b)); }
;                 ss += __shfl_xor(ss, 16); ss += __shfl_xor(ss, 32);
;                 if (fq == 0) __hip_atomic_fetch_add(RSS + row, ss, __ATOMIC_RELAXED, __HIP_MEMORY_SCOPE_AGENT);
;             }
.LBB0_782:
	s_or_b64 exec, exec, s[8:9]
	v_lshlrev_b32_e32 v34, 16, v216
	s_waitcnt lgkmcnt(0)
	v_and_b32_e32 v35, 0xffff0000, v216
	v_lshlrev_b32_e32 v36, 16, v217
	v_and_b32_e32 v37, 0xffff0000, v217
	v_pk_fma_f32 v[32:33], v[240:241], v[36:37], v[32:33] op_sel_hi:[0,1,1]
	v_pk_fma_f32 v[30:31], v[240:241], v[34:35], v[30:31] op_sel_hi:[0,1,1]
	v_lshlrev_b32_e32 v34, 16, v218
	v_and_b32_e32 v35, 0xffff0000, v218
	v_lshlrev_b32_e32 v36, 16, v219
	v_and_b32_e32 v37, 0xffff0000, v219
	v_pk_fma_f32 v[36:37], v[240:241], v[36:37], v[28:29] op_sel_hi:[0,1,1]
	v_pk_fma_f32 v[28:29], v[240:241], v[34:35], v[26:27] op_sel_hi:[0,1,1]
	v_mul_f32_e32 v26, v31, v31
	v_mul_f32_e32 v27, v33, v33
	v_fmac_f32_e32 v26, v30, v30
	v_fmac_f32_e32 v27, v32, v32
	v_add_f32_e32 v26, v26, v27
	v_mul_f32_e32 v27, v29, v29
	v_mul_f32_e32 v34, v37, v37
	v_fmac_f32_e32 v27, v28, v28
	v_fmac_f32_e32 v34, v36, v36
	v_add_f32_e32 v27, v27, v34
	v_add_f32_e32 v38, v26, v27
	v_lshl_add_u64 v[26:27], s[12:13], 0, v[100:101]
	v_lshl_add_u64 v[34:35], v[154:155], 1, v[26:27]
	v_cvt_pk_bf16_f32 v26, v30, v31
	v_cvt_pk_bf16_f32 v27, v32, v33
	v_cvt_pk_bf16_f32 v28, v28, v29
	v_cvt_pk_bf16_f32 v29, v36, v37
	global_store_dwordx4 v[34:35], v[26:29], off sc1
	s_nop 1
	v_lshlrev_b32_e32 v26, 16, v220
	v_and_b32_e32 v27, 0xffff0000, v220
	v_lshlrev_b32_e32 v28, 16, v221
	v_and_b32_e32 v29, 0xffff0000, v221
	v_pk_fma_f32 v[24:25], v[240:241], v[28:29], v[24:25] op_sel_hi:[0,1,1]
	v_pk_fma_f32 v[22:23], v[240:241], v[26:27], v[22:23] op_sel_hi:[0,1,1]
	v_lshlrev_b32_e32 v28, 16, v223
	v_and_b32_e32 v29, 0xffff0000, v223
	v_lshlrev_b32_e32 v26, 16, v222
	v_and_b32_e32 v27, 0xffff0000, v222
	v_pk_fma_f32 v[28:29], v[240:241], v[28:29], v[20:21] op_sel_hi:[0,1,1]
	v_mul_f32_e32 v20, v23, v23
	v_mul_f32_e32 v21, v25, v25
	v_pk_fma_f32 v[18:19], v[240:241], v[26:27], v[18:19] op_sel_hi:[0,1,1]
	v_fmac_f32_e32 v20, v22, v22
	v_fmac_f32_e32 v21, v24, v24
	v_add_f32_e32 v20, v20, v21
	v_mul_f32_e32 v21, v19, v19
	v_mul_f32_e32 v26, v29, v29
	v_fmac_f32_e32 v21, v18, v18
	v_fmac_f32_e32 v26, v28, v28
	v_add_f32_e32 v21, v21, v26
	v_add_f32_e32 v20, v20, v21
	v_add_f32_e32 v30, v38, v20
	v_mov_b32_e32 v31, v30
	s_nop 1
	v_permlane16_swap_b32_e32 v31, v30
	v_cvt_pk_bf16_f32 v20, v22, v23
	v_cvt_pk_bf16_f32 v22, v18, v19
	s_mov_b64 s[8:9], 0x100
	v_lshl_add_u64 v[26:27], v[34:35], 0, s[8:9]
	s_waitcnt lgkmcnt(0)
	v_add_f32_e32 v18, v30, v31
	v_mov_b32_e32 v19, v18
	s_nop 1
	v_permlane32_swap_b32_e32 v19, v18
	v_cvt_pk_bf16_f32 v21, v24, v25
	v_cvt_pk_bf16_f32 v23, v28, v29
	global_store_dwordx4 v[26:27], v[20:23], off sc1
	s_nop 1
	s_and_saveexec_b64 s[14:15], vcc
	s_cbranch_execz .LBB0_784
	v_lshl_add_u64 v[20:21], v[96:97], 2, s[10:11]
	s_waitcnt lgkmcnt(0)
	v_add_f32_e32 v18, v18, v19
	global_atomic_add_f32 v[20:21], v18, off
.LBB0_784:
	s_or_b64 exec, exec, s[14:15]
	v_lshlrev_b32_e32 v18, 16, v224
	s_waitcnt lgkmcnt(0)
	v_and_b32_e32 v19, 0xffff0000, v224
	v_lshlrev_b32_e32 v20, 16, v225
	v_and_b32_e32 v21, 0xffff0000, v225
	v_pk_fma_f32 v[16:17], v[244:245], v[20:21], v[16:17] op_sel_hi:[0,1,1]
	v_pk_fma_f32 v[14:15], v[244:245], v[18:19], v[14:15] op_sel_hi:[0,1,1]
	v_lshlrev_b32_e32 v18, 16, v226
	v_and_b32_e32 v19, 0xffff0000, v226
	v_lshlrev_b32_e32 v20, 16, v227
	v_and_b32_e32 v21, 0xffff0000, v227
	v_pk_fma_f32 v[20:21], v[244:245], v[20:21], v[12:13] op_sel_hi:[0,1,1]
	v_pk_fma_f32 v[12:13], v[244:245], v[18:19], v[10:11] op_sel_hi:[0,1,1]
	v_mul_f32_e32 v10, v15, v15
	v_mul_f32_e32 v11, v17, v17
	v_fmac_f32_e32 v10, v14, v14
	v_fmac_f32_e32 v11, v16, v16
	v_add_f32_e32 v10, v10, v11
	v_mul_f32_e32 v11, v13, v13
	v_mul_f32_e32 v18, v21, v21
	v_fmac_f32_e32 v11, v12, v12
	v_fmac_f32_e32 v18, v20, v20
	v_add_f32_e32 v11, v11, v18
	v_add_f32_e32 v22, v10, v11
	v_lshl_add_u64 v[10:11], s[12:13], 0, v[94:95]
	v_lshl_add_u64 v[18:19], v[154:155], 1, v[10:11]
	v_cvt_pk_bf16_f32 v10, v14, v15
	v_cvt_pk_bf16_f32 v11, v16, v17
	v_cvt_pk_bf16_f32 v12, v12, v13
	v_cvt_pk_bf16_f32 v13, v20, v21
	global_store_dwordx4 v[18:19], v[10:13], off sc1
	s_nop 1
	v_lshlrev_b32_e32 v10, 16, v232
	v_and_b32_e32 v11, 0xffff0000, v232
	v_lshlrev_b32_e32 v12, 16, v233
	v_and_b32_e32 v13, 0xffff0000, v233
	v_pk_fma_f32 v[8:9], v[244:245], v[12:13], v[8:9] op_sel_hi:[0,1,1]
	v_pk_fma_f32 v[6:7], v[244:245], v[10:11], v[6:7] op_sel_hi:[0,1,1]
	v_lshlrev_b32_e32 v12, 16, v235
	v_and_b32_e32 v13, 0xffff0000, v235
	v_lshlrev_b32_e32 v10, 16, v234
	v_and_b32_e32 v11, 0xffff0000, v234
	v_pk_fma_f32 v[12:13], v[244:245], v[12:13], v[4:5] op_sel_hi:[0,1,1]
	v_mul_f32_e32 v4, v7, v7
	v_mul_f32_e32 v5, v9, v9
	v_pk_fma_f32 v[2:3], v[244:245], v[10:11], v[2:3] op_sel_hi:[0,1,1]
	v_fmac_f32_e32 v4, v6, v6
	v_fmac_f32_e32 v5, v8, v8
	v_add_f32_e32 v4, v4, v5
	v_mul_f32_e32 v5, v3, v3
	v_mul_f32_e32 v10, v13, v13
	v_fmac_f32_e32 v5, v2, v2
	v_fmac_f32_e32 v10, v12, v12
	v_add_f32_e32 v5, v5, v10
	v_add_f32_e32 v4, v4, v5
	v_add_f32_e32 v14, v22, v4
	v_mov_b32_e32 v15, v14
	s_nop 1
	v_permlane16_swap_b32_e32 v15, v14
	v_cvt_pk_bf16_f32 v4, v6, v7
	v_cvt_pk_bf16_f32 v6, v2, v3
	v_lshl_add_u64 v[10:11], v[18:19], 0, s[8:9]
	v_cvt_pk_bf16_f32 v5, v8, v9
	s_waitcnt lgkmcnt(0)
	v_add_f32_e32 v2, v14, v15
	v_mov_b32_e32 v3, v2
	s_nop 1
	v_permlane32_swap_b32_e32 v3, v2
	v_cvt_pk_bf16_f32 v7, v12, v13
	global_store_dwordx4 v[10:11], v[4:7], off sc1
	s_nop 1
	s_and_saveexec_b64 s[8:9], vcc
	s_cbranch_execz .LBB0_786
	v_lshl_add_u64 v[4:5], v[90:91], 2, s[10:11]
	s_waitcnt lgkmcnt(0)
	v_add_f32_e32 v2, v2, v3
	global_atomic_add_f32 v[4:5], v2, off
